# adds scalar-FMA S5 scan block, hoisted LDS reads in GDN recurrence, rcp-based SiLU and pipelined ConvFFN epilogue fast path on top of pipelined GEMM loops
# speedup vs baseline: 1.0287x; 1.0287x over previous
.LBB0_442:
	s_or_b64 exec, exec, s[14:15]
	s_waitcnt lgkmcnt(0)
	s_barrier
	ds_read_b128 v[46:49], v203 offset:50176
	ds_read_b128 v[54:57], v203 offset:51456
	v_add_u32_e32 v0, 0x400, v204
	ds_read_b128 v[66:69], v203 offset:52736
	ds_read_b128 v[122:125], v203 offset:54016
	v_add_u32_e32 v50, 0x2000, v204
	s_waitcnt lgkmcnt(3)
	v_mfma_f32_16x16x32_bf16 v[58:61], v[46:49], v[36:39], 0
	v_mfma_f32_16x16x32_bf16 v[46:49], v[46:49], v[16:19], 0
	s_nop 7
	ds_write2_b32 v204, v58, v46 offset1:16
	ds_write2_b32 v204, v59, v47 offset0:128 offset1:144
	ds_write2_b32 v0, v60, v48 offset1:16
	ds_write2_b32 v0, v61, v49 offset0:128 offset1:144
	s_waitcnt lgkmcnt(6)
	v_mfma_f32_16x16x32_bf16 v[62:65], v[54:57], v[36:39], 0
	v_add_u32_e32 v0, 0x2400, v204
	v_mfma_f32_16x16x32_bf16 v[46:49], v[54:57], v[16:19], 0
	s_nop 7
	ds_write2_b32 v50, v62, v46 offset1:16
	ds_write2_b32 v50, v63, v47 offset0:128 offset1:144
	s_waitcnt lgkmcnt(7)
	v_mfma_f32_16x16x32_bf16 v[54:57], v[66:69], v[36:39], 0
	ds_write2_b32 v0, v64, v48 offset1:16
	ds_write2_b32 v0, v65, v49 offset0:128 offset1:144
	v_add_u32_e32 v0, 0x4000, v204
	v_mfma_f32_16x16x32_bf16 v[46:49], v[66:69], v[16:19], 0
	s_nop 7
	ds_write2_b32 v0, v54, v46 offset1:16
	ds_write2_b32 v0, v55, v47 offset0:128 offset1:144
	v_add_u32_e32 v0, 0x4400, v204
	s_waitcnt lgkmcnt(10)
	v_mfma_f32_16x16x32_bf16 v[58:61], v[122:125], v[36:39], 0
	ds_write2_b32 v0, v56, v48 offset1:16
	ds_write2_b32 v0, v57, v49 offset0:128 offset1:144
	v_add_u32_e32 v0, 0x6000, v204
	v_mfma_f32_16x16x32_bf16 v[46:49], v[122:125], v[16:19], 0
	s_nop 7
	ds_write2_b32 v0, v58, v46 offset1:16
	ds_write2_b32 v0, v59, v47 offset0:128 offset1:144
	v_add_u32_e32 v0, 0x6400, v204
	ds_write2_b32 v0, v60, v48 offset1:16
	ds_write2_b32 v0, v61, v49 offset0:128 offset1:144
	s_waitcnt lgkmcnt(0)
	s_barrier
	s_and_saveexec_b64 s[14:15], s[10:11]
	s_cbranch_execz .LBB0_438
	ds_read_b64 v[232:233], v97
	ds_read_b64 v[234:235], v97 offset:512
	ds_read_b64 v[236:237], v97 offset:1024
	ds_read_b64 v[238:239], v97 offset:1536
	ds_read_b64 v[240:241], v97 offset:2048
	ds_read_b64 v[242:243], v97 offset:2560
	ds_read_b64 v[244:245], v97 offset:3072
	ds_read_b64 v[246:247], v97 offset:3584
	ds_read_b64 v[54:55], v97 offset:4096
	ds_read_b64 v[56:57], v97 offset:4608
	ds_read_b64 v[58:59], v97 offset:5120
	ds_read_b64 v[60:61], v97 offset:5632
	ds_read_b64 v[62:63], v97 offset:6144
	ds_read_b64 v[64:65], v97 offset:6656
	ds_read_b64 v[46:47], v97 offset:7168
	s_waitcnt lgkmcnt(8)
	ds_read_b64 v[48:49], v97 offset:7680
	v_fma_f32 v50, -v52, v45, v232
	v_fma_f32 v51, v52, v44, v233
	v_fma_f32 v44, v2, v44, v50
	v_fma_f32 v45, v2, v45, v51
	v_cvt_pk_bf16_f32 v0, v44, v45
	ds_write_b32 v229, v0 offset:32768
	v_fma_f32 v50, -v52, v45, v234
	v_fma_f32 v51, v52, v44, v235
	v_fma_f32 v44, v2, v44, v50
	v_fma_f32 v45, v2, v45, v51
	v_cvt_pk_bf16_f32 v66, v44, v45
	ds_write_b32 v229, v66 offset:33040
	v_fma_f32 v50, -v52, v45, v236
	v_fma_f32 v51, v52, v44, v237
	v_fma_f32 v44, v2, v44, v50
	v_fma_f32 v45, v2, v45, v51
	v_cvt_pk_bf16_f32 v0, v44, v45
	ds_write_b32 v229, v0 offset:33312
	v_fma_f32 v50, -v52, v45, v238
	v_fma_f32 v51, v52, v44, v239
	v_fma_f32 v44, v2, v44, v50
	v_fma_f32 v45, v2, v45, v51
	v_cvt_pk_bf16_f32 v66, v44, v45
	ds_write_b32 v229, v66 offset:33584
	v_fma_f32 v50, -v52, v45, v240
	v_fma_f32 v51, v52, v44, v241
	v_fma_f32 v44, v2, v44, v50
	v_fma_f32 v45, v2, v45, v51
	v_cvt_pk_bf16_f32 v0, v44, v45
	ds_write_b32 v229, v0 offset:33856
	v_fma_f32 v50, -v52, v45, v242
	v_fma_f32 v51, v52, v44, v243
	v_fma_f32 v44, v2, v44, v50
	v_fma_f32 v45, v2, v45, v51
	v_cvt_pk_bf16_f32 v66, v44, v45
	ds_write_b32 v229, v66 offset:34128
	v_fma_f32 v50, -v52, v45, v244
	v_fma_f32 v51, v52, v44, v245
	v_fma_f32 v44, v2, v44, v50
	v_fma_f32 v45, v2, v45, v51
	v_cvt_pk_bf16_f32 v0, v44, v45
	s_waitcnt lgkmcnt(8)
	ds_write_b32 v229, v0 offset:34400
	v_fma_f32 v50, -v52, v45, v246
	v_fma_f32 v51, v52, v44, v247
	v_fma_f32 v44, v2, v44, v50
	v_fma_f32 v45, v2, v45, v51
	v_cvt_pk_bf16_f32 v66, v44, v45
	ds_write_b32 v229, v66 offset:34672
	ds_read_b64 v[232:233], v97 offset:8192
	ds_read_b64 v[234:235], v97 offset:8704
	ds_read_b64 v[236:237], v97 offset:9216
	ds_read_b64 v[238:239], v97 offset:9728
	ds_read_b64 v[240:241], v97 offset:10240
	s_waitcnt lgkmcnt(8)
	ds_read_b64 v[242:243], v97 offset:10752
	ds_read_b64 v[244:245], v97 offset:11264
	ds_read_b64 v[246:247], v97 offset:11776
	v_fma_f32 v50, -v52, v45, v54
	v_fma_f32 v51, v52, v44, v55
	v_fma_f32 v44, v2, v44, v50
	v_fma_f32 v45, v2, v45, v51
	v_cvt_pk_bf16_f32 v0, v44, v45
	ds_write_b32 v229, v0 offset:34944
	v_fma_f32 v50, -v52, v45, v56
	v_fma_f32 v51, v52, v44, v57
	v_fma_f32 v44, v2, v44, v50
	v_fma_f32 v45, v2, v45, v51
	v_cvt_pk_bf16_f32 v66, v44, v45
	ds_write_b32 v229, v66 offset:35216
	v_fma_f32 v50, -v52, v45, v58
	v_fma_f32 v51, v52, v44, v59
	v_fma_f32 v44, v2, v44, v50
	v_fma_f32 v45, v2, v45, v51
	v_cvt_pk_bf16_f32 v0, v44, v45
	ds_write_b32 v229, v0 offset:35488
	v_fma_f32 v50, -v52, v45, v60
	v_fma_f32 v51, v52, v44, v61
	v_fma_f32 v44, v2, v44, v50
	v_fma_f32 v45, v2, v45, v51
	v_cvt_pk_bf16_f32 v66, v44, v45
	ds_write_b32 v229, v66 offset:35760
	v_fma_f32 v50, -v52, v45, v62
	v_fma_f32 v51, v52, v44, v63
	v_fma_f32 v44, v2, v44, v50
	v_fma_f32 v45, v2, v45, v51
	v_cvt_pk_bf16_f32 v0, v44, v45
	s_waitcnt lgkmcnt(8)
	ds_write_b32 v229, v0 offset:36032
	v_fma_f32 v50, -v52, v45, v64
	v_fma_f32 v51, v52, v44, v65
	v_fma_f32 v44, v2, v44, v50
	v_fma_f32 v45, v2, v45, v51
	v_cvt_pk_bf16_f32 v66, v44, v45
	ds_write_b32 v229, v66 offset:36304
	v_fma_f32 v50, -v52, v45, v46
	v_fma_f32 v51, v52, v44, v47
	v_fma_f32 v44, v2, v44, v50
	v_fma_f32 v45, v2, v45, v51
	v_cvt_pk_bf16_f32 v0, v44, v45
	ds_write_b32 v229, v0 offset:36576
	v_fma_f32 v50, -v52, v45, v48
	v_fma_f32 v51, v52, v44, v49
	v_fma_f32 v44, v2, v44, v50
	v_fma_f32 v45, v2, v45, v51
	v_cvt_pk_bf16_f32 v66, v44, v45
	ds_write_b32 v229, v66 offset:36848
	ds_read_b64 v[54:55], v97 offset:12288
	ds_read_b64 v[56:57], v97 offset:12800
	ds_read_b64 v[58:59], v97 offset:13312
	s_waitcnt lgkmcnt(8)
	ds_read_b64 v[60:61], v97 offset:13824
	ds_read_b64 v[62:63], v97 offset:14336
	ds_read_b64 v[64:65], v97 offset:14848
	ds_read_b64 v[46:47], v97 offset:15360
	ds_read_b64 v[48:49], v97 offset:15872
	v_fma_f32 v50, -v52, v45, v232
	v_fma_f32 v51, v52, v44, v233
	v_fma_f32 v44, v2, v44, v50
	v_fma_f32 v45, v2, v45, v51
	v_cvt_pk_bf16_f32 v0, v44, v45
	ds_write_b32 v229, v0 offset:37120
	v_fma_f32 v50, -v52, v45, v234
	v_fma_f32 v51, v52, v44, v235
	v_fma_f32 v44, v2, v44, v50
	v_fma_f32 v45, v2, v45, v51
	v_cvt_pk_bf16_f32 v66, v44, v45
	ds_write_b32 v229, v66 offset:37392
	v_fma_f32 v50, -v52, v45, v236
	v_fma_f32 v51, v52, v44, v237
	v_fma_f32 v44, v2, v44, v50
	v_fma_f32 v45, v2, v45, v51
	v_cvt_pk_bf16_f32 v0, v44, v45
	s_waitcnt lgkmcnt(8)
	ds_write_b32 v229, v0 offset:37664
	v_fma_f32 v50, -v52, v45, v238
	v_fma_f32 v51, v52, v44, v239
	v_fma_f32 v44, v2, v44, v50
	v_fma_f32 v45, v2, v45, v51
	v_cvt_pk_bf16_f32 v66, v44, v45
	ds_write_b32 v229, v66 offset:37936
	v_fma_f32 v50, -v52, v45, v240
	v_fma_f32 v51, v52, v44, v241
	v_fma_f32 v44, v2, v44, v50
	v_fma_f32 v45, v2, v45, v51
	v_cvt_pk_bf16_f32 v0, v44, v45
	ds_write_b32 v229, v0 offset:38208
	v_fma_f32 v50, -v52, v45, v242
	v_fma_f32 v51, v52, v44, v243
	v_fma_f32 v44, v2, v44, v50
	v_fma_f32 v45, v2, v45, v51
	v_cvt_pk_bf16_f32 v66, v44, v45
	ds_write_b32 v229, v66 offset:38480
	v_fma_f32 v50, -v52, v45, v244
	v_fma_f32 v51, v52, v44, v245
	v_fma_f32 v44, v2, v44, v50
	v_fma_f32 v45, v2, v45, v51
	v_cvt_pk_bf16_f32 v0, v44, v45
	ds_write_b32 v229, v0 offset:38752
	v_fma_f32 v50, -v52, v45, v246
	v_fma_f32 v51, v52, v44, v247
	v_fma_f32 v44, v2, v44, v50
	v_fma_f32 v45, v2, v45, v51
	v_cvt_pk_bf16_f32 v66, v44, v45
	ds_write_b32 v229, v66 offset:39024
	ds_read_b64 v[232:233], v97 offset:16384
	s_waitcnt lgkmcnt(8)
	ds_read_b64 v[234:235], v97 offset:16896
	ds_read_b64 v[236:237], v97 offset:17408
	ds_read_b64 v[238:239], v97 offset:17920
	ds_read_b64 v[240:241], v97 offset:18432
	ds_read_b64 v[242:243], v97 offset:18944
	ds_read_b64 v[244:245], v97 offset:19456
	ds_read_b64 v[246:247], v97 offset:19968
	v_fma_f32 v50, -v52, v45, v54
	v_fma_f32 v51, v52, v44, v55
	v_fma_f32 v44, v2, v44, v50
	v_fma_f32 v45, v2, v45, v51
	v_cvt_pk_bf16_f32 v0, v44, v45
	s_waitcnt lgkmcnt(8)
	ds_write_b32 v229, v0 offset:39296
	v_fma_f32 v50, -v52, v45, v56
	v_fma_f32 v51, v52, v44, v57
	v_fma_f32 v44, v2, v44, v50
	v_fma_f32 v45, v2, v45, v51
	v_cvt_pk_bf16_f32 v66, v44, v45
	ds_write_b32 v229, v66 offset:39568
	v_fma_f32 v50, -v52, v45, v58
	v_fma_f32 v51, v52, v44, v59
	v_fma_f32 v44, v2, v44, v50
	v_fma_f32 v45, v2, v45, v51
	v_cvt_pk_bf16_f32 v0, v44, v45
	ds_write_b32 v229, v0 offset:39840
	v_fma_f32 v50, -v52, v45, v60
	v_fma_f32 v51, v52, v44, v61
	v_fma_f32 v44, v2, v44, v50
	v_fma_f32 v45, v2, v45, v51
	v_cvt_pk_bf16_f32 v66, v44, v45
	ds_write_b32 v229, v66 offset:40112
	v_fma_f32 v50, -v52, v45, v62
	v_fma_f32 v51, v52, v44, v63
	v_fma_f32 v44, v2, v44, v50
	v_fma_f32 v45, v2, v45, v51
	v_cvt_pk_bf16_f32 v0, v44, v45
	ds_write_b32 v229, v0 offset:40384
	v_fma_f32 v50, -v52, v45, v64
	v_fma_f32 v51, v52, v44, v65
	v_fma_f32 v44, v2, v44, v50
	v_fma_f32 v45, v2, v45, v51
	v_cvt_pk_bf16_f32 v66, v44, v45
	ds_write_b32 v229, v66 offset:40656
	v_fma_f32 v50, -v52, v45, v46
	v_fma_f32 v51, v52, v44, v47
	v_fma_f32 v44, v2, v44, v50
	v_fma_f32 v45, v2, v45, v51
	v_cvt_pk_bf16_f32 v0, v44, v45
	ds_write_b32 v229, v0 offset:40928
	v_fma_f32 v50, -v52, v45, v48
	v_fma_f32 v51, v52, v44, v49
	v_fma_f32 v44, v2, v44, v50
	v_fma_f32 v45, v2, v45, v51
	v_cvt_pk_bf16_f32 v66, v44, v45
	s_waitcnt lgkmcnt(8)
	ds_write_b32 v229, v66 offset:41200
	ds_read_b64 v[54:55], v97 offset:20480
	ds_read_b64 v[56:57], v97 offset:20992
	ds_read_b64 v[58:59], v97 offset:21504
	ds_read_b64 v[60:61], v97 offset:22016
	ds_read_b64 v[62:63], v97 offset:22528
	ds_read_b64 v[64:65], v97 offset:23040
	s_waitcnt lgkmcnt(8)
	ds_read_b64 v[46:47], v97 offset:23552
	ds_read_b64 v[48:49], v97 offset:24064
	v_fma_f32 v50, -v52, v45, v232
	v_fma_f32 v51, v52, v44, v233
	v_fma_f32 v44, v2, v44, v50
	v_fma_f32 v45, v2, v45, v51
	v_cvt_pk_bf16_f32 v0, v44, v45
	ds_write_b32 v229, v0 offset:41472
	v_fma_f32 v50, -v52, v45, v234
	v_fma_f32 v51, v52, v44, v235
	v_fma_f32 v44, v2, v44, v50
	v_fma_f32 v45, v2, v45, v51
	v_cvt_pk_bf16_f32 v66, v44, v45
	ds_write_b32 v229, v66 offset:41744
	v_fma_f32 v50, -v52, v45, v236
	v_fma_f32 v51, v52, v44, v237
	v_fma_f32 v44, v2, v44, v50
	v_fma_f32 v45, v2, v45, v51
	v_cvt_pk_bf16_f32 v0, v44, v45
	ds_write_b32 v229, v0 offset:42016
	v_fma_f32 v50, -v52, v45, v238
	v_fma_f32 v51, v52, v44, v239
	v_fma_f32 v44, v2, v44, v50
	v_fma_f32 v45, v2, v45, v51
	v_cvt_pk_bf16_f32 v66, v44, v45
	ds_write_b32 v229, v66 offset:42288
	v_fma_f32 v50, -v52, v45, v240
	v_fma_f32 v51, v52, v44, v241
	v_fma_f32 v44, v2, v44, v50
	v_fma_f32 v45, v2, v45, v51
	v_cvt_pk_bf16_f32 v0, v44, v45
	ds_write_b32 v229, v0 offset:42560
	v_fma_f32 v50, -v52, v45, v242
	v_fma_f32 v51, v52, v44, v243
	v_fma_f32 v44, v2, v44, v50
	v_fma_f32 v45, v2, v45, v51
	v_cvt_pk_bf16_f32 v66, v44, v45
	s_waitcnt lgkmcnt(8)
	ds_write_b32 v229, v66 offset:42832
	v_fma_f32 v50, -v52, v45, v244
	v_fma_f32 v51, v52, v44, v245
	v_fma_f32 v44, v2, v44, v50
	v_fma_f32 v45, v2, v45, v51
	v_cvt_pk_bf16_f32 v0, v44, v45
	ds_write_b32 v229, v0 offset:43104
	v_fma_f32 v50, -v52, v45, v246
	v_fma_f32 v51, v52, v44, v247
	v_fma_f32 v44, v2, v44, v50
	v_fma_f32 v45, v2, v45, v51
	v_cvt_pk_bf16_f32 v66, v44, v45
	ds_write_b32 v229, v66 offset:43376
	ds_read_b64 v[232:233], v97 offset:24576
	ds_read_b64 v[234:235], v97 offset:25088
	ds_read_b64 v[236:237], v97 offset:25600
	ds_read_b64 v[238:239], v97 offset:26112
	s_waitcnt lgkmcnt(8)
	ds_read_b64 v[240:241], v97 offset:26624
	ds_read_b64 v[242:243], v97 offset:27136
	ds_read_b64 v[244:245], v97 offset:27648
	ds_read_b64 v[246:247], v97 offset:28160
	v_fma_f32 v50, -v52, v45, v54
	v_fma_f32 v51, v52, v44, v55
	v_fma_f32 v44, v2, v44, v50
	v_fma_f32 v45, v2, v45, v51
	v_cvt_pk_bf16_f32 v0, v44, v45
	ds_write_b32 v229, v0 offset:43648
	v_fma_f32 v50, -v52, v45, v56
	v_fma_f32 v51, v52, v44, v57
	v_fma_f32 v44, v2, v44, v50
	v_fma_f32 v45, v2, v45, v51
	v_cvt_pk_bf16_f32 v66, v44, v45
	ds_write_b32 v229, v66 offset:43920
	v_fma_f32 v50, -v52, v45, v58
	v_fma_f32 v51, v52, v44, v59
	v_fma_f32 v44, v2, v44, v50
	v_fma_f32 v45, v2, v45, v51
	v_cvt_pk_bf16_f32 v0, v44, v45
	ds_write_b32 v229, v0 offset:44192
	v_fma_f32 v50, -v52, v45, v60
	v_fma_f32 v51, v52, v44, v61
	v_fma_f32 v44, v2, v44, v50
	v_fma_f32 v45, v2, v45, v51
	v_cvt_pk_bf16_f32 v66, v44, v45
	s_waitcnt lgkmcnt(8)
	ds_write_b32 v229, v66 offset:44464
	v_fma_f32 v50, -v52, v45, v62
	v_fma_f32 v51, v52, v44, v63
	v_fma_f32 v44, v2, v44, v50
	v_fma_f32 v45, v2, v45, v51
	v_cvt_pk_bf16_f32 v0, v44, v45
	ds_write_b32 v229, v0 offset:44736
	v_fma_f32 v50, -v52, v45, v64
	v_fma_f32 v51, v52, v44, v65
	v_fma_f32 v44, v2, v44, v50
	v_fma_f32 v45, v2, v45, v51
	v_cvt_pk_bf16_f32 v66, v44, v45
	ds_write_b32 v229, v66 offset:45008
	v_fma_f32 v50, -v52, v45, v46
	v_fma_f32 v51, v52, v44, v47
	v_fma_f32 v44, v2, v44, v50
	v_fma_f32 v45, v2, v45, v51
	v_cvt_pk_bf16_f32 v0, v44, v45
	ds_write_b32 v229, v0 offset:45280
	v_fma_f32 v50, -v52, v45, v48
	v_fma_f32 v51, v52, v44, v49
	v_fma_f32 v44, v2, v44, v50
	v_fma_f32 v45, v2, v45, v51
	v_cvt_pk_bf16_f32 v66, v44, v45
	ds_write_b32 v229, v66 offset:45552
	ds_read_b64 v[54:55], v97 offset:28672
	ds_read_b64 v[56:57], v97 offset:29184
	s_waitcnt lgkmcnt(8)
	ds_read_b64 v[58:59], v97 offset:29696
	ds_read_b64 v[60:61], v97 offset:30208
	ds_read_b64 v[62:63], v97 offset:30720
	ds_read_b64 v[64:65], v97 offset:31232
	ds_read_b64 v[46:47], v97 offset:31744
	ds_read_b64 v[48:49], v97 offset:32256
	v_fma_f32 v50, -v52, v45, v232
	v_fma_f32 v51, v52, v44, v233
	v_fma_f32 v44, v2, v44, v50
	v_fma_f32 v45, v2, v45, v51
	v_cvt_pk_bf16_f32 v0, v44, v45
	ds_write_b32 v229, v0 offset:45824
	v_fma_f32 v50, -v52, v45, v234
	v_fma_f32 v51, v52, v44, v235
	v_fma_f32 v44, v2, v44, v50
	v_fma_f32 v45, v2, v45, v51
	v_cvt_pk_bf16_f32 v66, v44, v45
	s_waitcnt lgkmcnt(8)
	ds_write_b32 v229, v66 offset:46096
	v_fma_f32 v50, -v52, v45, v236
	v_fma_f32 v51, v52, v44, v237
	v_fma_f32 v44, v2, v44, v50
	v_fma_f32 v45, v2, v45, v51
	v_cvt_pk_bf16_f32 v0, v44, v45
	ds_write_b32 v229, v0 offset:46368
	v_fma_f32 v50, -v52, v45, v238
	v_fma_f32 v51, v52, v44, v239
	v_fma_f32 v44, v2, v44, v50
	v_fma_f32 v45, v2, v45, v51
	v_cvt_pk_bf16_f32 v66, v44, v45
	ds_write_b32 v229, v66 offset:46640
	v_fma_f32 v50, -v52, v45, v240
	v_fma_f32 v51, v52, v44, v241
	v_fma_f32 v44, v2, v44, v50
	v_fma_f32 v45, v2, v45, v51
	v_cvt_pk_bf16_f32 v0, v44, v45
	ds_write_b32 v229, v0 offset:46912
	v_fma_f32 v50, -v52, v45, v242
	v_fma_f32 v51, v52, v44, v243
	v_fma_f32 v44, v2, v44, v50
	v_fma_f32 v45, v2, v45, v51
	v_cvt_pk_bf16_f32 v66, v44, v45
	ds_write_b32 v229, v66 offset:47184
	v_fma_f32 v50, -v52, v45, v244
	v_fma_f32 v51, v52, v44, v245
	v_fma_f32 v44, v2, v44, v50
	v_fma_f32 v45, v2, v45, v51
	v_cvt_pk_bf16_f32 v0, v44, v45
	ds_write_b32 v229, v0 offset:47456
	v_fma_f32 v50, -v52, v45, v246
	v_fma_f32 v51, v52, v44, v247
	v_fma_f32 v44, v2, v44, v50
	v_fma_f32 v45, v2, v45, v51
	v_cvt_pk_bf16_f32 v66, v44, v45
	ds_write_b32 v229, v66 offset:47728
	v_fma_f32 v50, -v52, v45, v54
	v_fma_f32 v51, v52, v44, v55
	v_fma_f32 v44, v2, v44, v50
	v_fma_f32 v45, v2, v45, v51
	v_cvt_pk_bf16_f32 v0, v44, v45
	s_waitcnt lgkmcnt(8)
	ds_write_b32 v229, v0 offset:48000
	v_fma_f32 v50, -v52, v45, v56
	v_fma_f32 v51, v52, v44, v57
	v_fma_f32 v44, v2, v44, v50
	v_fma_f32 v45, v2, v45, v51
	v_cvt_pk_bf16_f32 v66, v44, v45
	ds_write_b32 v229, v66 offset:48272
	v_fma_f32 v50, -v52, v45, v58
	v_fma_f32 v51, v52, v44, v59
	v_fma_f32 v44, v2, v44, v50
	v_fma_f32 v45, v2, v45, v51
	v_cvt_pk_bf16_f32 v0, v44, v45
	ds_write_b32 v229, v0 offset:48544
	v_fma_f32 v50, -v52, v45, v60
	v_fma_f32 v51, v52, v44, v61
	v_fma_f32 v44, v2, v44, v50
	v_fma_f32 v45, v2, v45, v51
	v_cvt_pk_bf16_f32 v66, v44, v45
	ds_write_b32 v229, v66 offset:48816
	v_fma_f32 v50, -v52, v45, v62
	v_fma_f32 v51, v52, v44, v63
	v_fma_f32 v44, v2, v44, v50
	v_fma_f32 v45, v2, v45, v51
	v_cvt_pk_bf16_f32 v0, v44, v45
	ds_write_b32 v229, v0 offset:49088
	v_fma_f32 v50, -v52, v45, v64
	v_fma_f32 v51, v52, v44, v65
	v_fma_f32 v44, v2, v44, v50
	v_fma_f32 v45, v2, v45, v51
	v_cvt_pk_bf16_f32 v66, v44, v45
	ds_write_b32 v229, v66 offset:49360
	v_fma_f32 v50, -v52, v45, v46
	v_fma_f32 v51, v52, v44, v47
	v_fma_f32 v44, v2, v44, v50
	v_fma_f32 v45, v2, v45, v51
	v_cvt_pk_bf16_f32 v0, v44, v45
	ds_write_b32 v229, v0 offset:49632
	v_fma_f32 v50, -v52, v45, v48
	v_fma_f32 v51, v52, v44, v49
	v_fma_f32 v44, v2, v44, v50
	v_fma_f32 v45, v2, v45, v51
	v_cvt_pk_bf16_f32 v66, v44, v45
	s_waitcnt lgkmcnt(8)
	ds_write_b32 v229, v66 offset:49904
	s_branch .LBB0_438

.LBB0_555:
	v_add_u32_e32 v208, v122, v177
	ds_read_b128 v[210:213], v208
	ds_read_b128 v[214:217], v208 offset:4352
	ds_read_b128 v[220:223], v208 offset:64
	ds_read_b128 v[224:227], v208 offset:4416
	ds_read_b128 v[230:233], v208 offset:128
	ds_read_b128 v[234:237], v208 offset:4480
	ds_read_b128 v[238:241], v208 offset:192
	ds_read_b128 v[242:245], v208 offset:4544
	s_waitcnt vmcnt(22) lgkmcnt(7)
	v_mfma_f32_16x16x32_bf16 v[76:79], v[32:35], v[210:213], 0
	s_waitcnt vmcnt(21)
	v_mfma_f32_16x16x32_bf16 v[72:75], v[210:213], v[44:47], 0
	s_waitcnt lgkmcnt(6)
	v_mfma_f32_16x16x32_bf16 v[32:35], v[32:35], v[214:217], 0
	v_mfma_f32_16x16x32_bf16 v[44:47], v[214:217], v[44:47], 0
	s_waitcnt vmcnt(20) lgkmcnt(5)
	v_mfma_f32_16x16x32_bf16 v[76:79], v[12:15], v[220:223], v[76:79]
	s_waitcnt vmcnt(18)
	v_mfma_f32_16x16x32_bf16 v[72:75], v[220:223], v[28:31], v[72:75]
	s_waitcnt lgkmcnt(4)
	v_mfma_f32_16x16x32_bf16 v[12:15], v[12:15], v[224:227], v[32:35]
	s_nop 2
	v_mfma_f32_16x16x32_bf16 v[28:31], v[224:227], v[28:31], v[44:47]
	s_waitcnt lgkmcnt(3)
	v_mfma_f32_16x16x32_bf16 v[44:47], v[16:19], v[230:233], v[76:79]
	s_waitcnt vmcnt(16)
	v_mfma_f32_16x16x32_bf16 v[32:35], v[230:233], v[24:27], v[72:75]
	s_nop 2
	s_waitcnt lgkmcnt(2)
	v_mfma_f32_16x16x32_bf16 v[12:15], v[16:19], v[234:237], v[12:15]
	v_mfma_f32_16x16x32_bf16 v[16:19], v[234:237], v[24:27], v[28:31]
	s_waitcnt lgkmcnt(1)
	v_mfma_f32_16x16x32_bf16 v[28:31], v[0:3], v[238:241], v[44:47]
	s_waitcnt vmcnt(15)
	v_mfma_f32_16x16x32_bf16 v[72:75], v[238:241], v[4:7], v[32:35]
	s_waitcnt lgkmcnt(0)
	v_mfma_f32_16x16x32_bf16 v[0:3], v[0:3], v[242:245], v[12:15]
	v_mfma_f32_16x16x32_bf16 v[76:79], v[242:245], v[4:7], v[16:19]
	s_waitcnt vmcnt(14)
	v_lshlrev_b32_e32 v4, 16, v186
	s_waitcnt vmcnt(13)
	v_lshlrev_b32_e32 v5, 16, v188
	s_waitcnt vmcnt(12)
	v_lshlrev_b32_e32 v6, 16, v185
	s_waitcnt vmcnt(11)
	v_lshlrev_b32_e32 v7, 16, v89
	v_sub_f32_e32 v4, v4, v28
	v_sub_f32_e32 v5, v5, v29
	v_sub_f32_e32 v6, v6, v30
	v_sub_f32_e32 v7, v7, v31
	v_cvt_pk_bf16_f32 v4, v4, v5
	v_cvt_pk_bf16_f32 v5, v6, v7
	ds_write_b64 v182, v[4:5] offset:8704
	s_waitcnt vmcnt(7)
	v_lshlrev_b32_e32 v4, 16, v91
	v_sub_f32_e32 v0, v4, v0
	v_lshlrev_b32_e32 v4, 16, v187
	v_sub_f32_e32 v1, v4, v1
	v_lshlrev_b32_e32 v4, 16, v189
	v_sub_f32_e32 v2, v4, v2
	v_lshlrev_b32_e32 v4, 16, v190
	v_sub_f32_e32 v3, v4, v3
	v_cvt_pk_bf16_f32 v0, v0, v1
	v_cvt_pk_bf16_f32 v1, v2, v3
	ds_write_b64 v182, v[0:1] offset:11008
	v_lshl_add_u64 v[144:145], s[16:17], 0, v[134:135]
	s_mov_b32 s22, 0x16000
	v_add_co_u32_e32 v0, vcc, s22, v144
	s_mov_b32 s22, 0x1a000
	s_nop 0
	v_addc_co_u32_e32 v1, vcc, 0, v145, vcc
	v_add_co_u32_e32 v4, vcc, s22, v144
	v_lshl_add_u64 v[146:147], s[16:17], 0, v[80:81]
	s_nop 0
	v_addc_co_u32_e32 v5, vcc, 0, v145, vcc
	v_add_co_u32_e32 v90, vcc, s45, v146
	v_lshl_add_u64 v[152:153], s[16:17], 0, v[84:85]
	s_nop 0
	v_addc_co_u32_e32 v91, vcc, 0, v147, vcc
	v_add_co_u32_e32 v92, vcc, s45, v152
	global_load_dwordx4 v[32:35], v[0:1], off
	global_load_dwordx4 v[44:47], v[4:5], off
	global_load_dwordx4 v[12:15], v[0:1], off offset:64
	global_load_dwordx4 v[28:31], v[4:5], off offset:64
	global_load_dwordx4 v[16:19], v[0:1], off offset:128
	global_load_dwordx4 v[24:27], v[4:5], off offset:128
	s_nop 0
	global_load_dwordx4 v[0:3], v[0:1], off offset:192
	s_nop 0
	global_load_dwordx4 v[4:7], v[4:5], off offset:192
	v_addc_co_u32_e32 v93, vcc, 0, v153, vcc
	v_lshl_add_u64 v[150:151], s[16:17], 0, v[82:83]
	global_load_ushort v186, v[90:91], off
	global_load_ushort v188, v[90:91], off offset:256
	global_load_ushort v185, v[90:91], off offset:512
	global_load_ushort v89, v[90:91], off offset:768
	s_nop 0
	global_load_ushort v91, v[90:91], off offset:32
	v_lshl_add_u64 v[148:149], s[16:17], 0, v[112:113]
	global_load_ushort v187, v[92:93], off offset:32
	v_add_co_u32_e32 v92, vcc, s45, v150
	s_nop 1
	v_addc_co_u32_e32 v93, vcc, 0, v151, vcc
	global_load_ushort v189, v[92:93], off offset:32
	v_add_co_u32_e32 v92, vcc, s45, v148
	s_nop 1
	v_addc_co_u32_e32 v93, vcc, 0, v149, vcc
	global_load_ushort v190, v[92:93], off offset:32
	global_load_dword v90, v113, s[18:19]
	s_waitcnt lgkmcnt(0)
	s_barrier
	v_add_u32_e32 v191, v122, v178
	ds_read_b128 v[92:95], v191 offset:8704
	ds_read_b128 v[192:195], v191 offset:11008
	s_waitcnt vmcnt(22) lgkmcnt(1)
	v_mfma_f32_16x16x32_bf16 v[72:75], v[92:95], v[52:55], v[72:75]
	ds_read_b128 v[196:199], v191 offset:11072
	s_waitcnt lgkmcnt(1)
	v_mfma_f32_16x16x32_bf16 v[52:55], v[192:195], v[52:55], v[76:79]
	s_nop 2
	ds_read_b128 v[76:79], v191 offset:8768
	s_waitcnt vmcnt(21) lgkmcnt(0)
	v_mfma_f32_16x16x32_bf16 v[72:75], v[76:79], v[48:51], v[72:75]
	v_mfma_f32_16x16x32_bf16 v[200:203], v[196:199], v[48:51], v[52:55]
	s_waitcnt vmcnt(5)
	v_pk_mul_f32 v[50:51], v[58:59], v[88:89] op_sel_hi:[1,0]
	v_pk_mul_f32 v[48:49], v[56:57], v[88:89] op_sel_hi:[1,0]
	v_pk_mul_f32 v[54:55], v[66:67], v[88:89] op_sel_hi:[1,0]
	v_pk_mul_f32 v[52:53], v[64:65], v[88:89] op_sel_hi:[1,0]
	v_mfma_f32_16x16x32_bf16 v[48:51], v[40:43], v[92:95], v[48:51]
	s_nop 0
	v_mfma_f32_16x16x32_bf16 v[40:43], v[40:43], v[192:195], v[52:55]
	v_mfma_f32_16x16x32_bf16 v[64:67], v[36:39], v[76:79], v[48:51]
	v_mfma_f32_16x16x32_bf16 v[56:59], v[36:39], v[196:199], v[40:43]
	v_mul_f32_e64 v38, v70, v88
	v_mul_f32_e64 v39, v71, v88
	v_pk_mul_f32 v[36:37], v[68:69], v[88:89] op_sel_hi:[1,0]
	s_nop 2
	v_pk_mul_f32 v[42:43], v[62:63], v[88:89] op_sel_hi:[1,0]
	v_pk_mul_f32 v[40:41], v[60:61], v[88:89] op_sel_hi:[1,0]
	v_mfma_f32_16x16x32_bf16 v[36:39], v[8:11], v[92:95], v[36:39]
	s_nop 0
	v_mfma_f32_16x16x32_bf16 v[8:11], v[8:11], v[192:195], v[40:43]
	v_mfma_f32_16x16x32_bf16 v[68:71], v[20:23], v[76:79], v[36:39]
	v_mfma_f32_16x16x32_bf16 v[60:63], v[20:23], v[196:199], v[8:11]
	v_lshl_add_u64 v[94:95], s[16:17], 0, v[136:137]
	s_mov_b32 s22, 0x22000
	s_nop 3
	v_add_co_u32_e32 v8, vcc, s22, v94
	v_lshl_add_u64 v[92:93], s[16:17], 0, v[138:139]
	s_nop 0
	v_addc_co_u32_e32 v9, vcc, 0, v95, vcc
	s_mov_b32 s22, 0x1e000
	v_add_co_u32_e32 v20, vcc, s22, v92
	s_nop 1
	v_addc_co_u32_e32 v21, vcc, 0, v93, vcc
	global_load_dwordx4 v[52:55], v[8:9], off
	global_load_dwordx4 v[48:51], v[8:9], off offset:64
	global_load_dwordx4 v[40:43], v[20:21], off
	global_load_dwordx4 v[36:39], v[20:21], off offset:64
	s_nop 0
	global_load_dwordx4 v[8:11], v[20:21], off offset:2048
	s_nop 0
	global_load_dwordx4 v[20:23], v[20:21], off offset:2112
	s_nop 0
	global_store_dwordx4 v[86:87], v[72:75], off
	global_store_dwordx4 v[86:87], v[200:203], off offset:64
	v_cvt_pk_bf16_f32 v76, v68, v69
	v_cvt_pk_bf16_f32 v72, v64, v65
	v_cvt_pk_bf16_f32 v73, v66, v67
	v_cvt_pk_bf16_f32 v77, v70, v71
	v_cvt_pk_bf16_f32 v74, v56, v57
	v_cvt_pk_bf16_f32 v75, v58, v59
	ds_write2_b64 v184, v[72:73], v[76:77] offset1:4
	v_cvt_pk_bf16_f32 v72, v60, v61
	v_cvt_pk_bf16_f32 v73, v62, v63
	v_add_u32_e32 v143, 0x1000, v184
	ds_write2_b64 v143, v[74:75], v[72:73] offset0:32 offset1:36
	s_waitcnt lgkmcnt(0)
	s_barrier
	ds_read_b128 v[210:213], v208
	ds_read_b128 v[214:217], v208 offset:64
	ds_read_b128 v[220:223], v208 offset:4352
	ds_read_b128 v[224:227], v208 offset:4416
	ds_read_b128 v[230:233], v208 offset:128
	ds_read_b128 v[234:237], v208 offset:4480
	ds_read_b128 v[238:241], v208 offset:192
	ds_read_b128 v[242:245], v208 offset:4544
	s_waitcnt lgkmcnt(7)
	v_mfma_f32_16x16x32_bf16 v[76:79], v[32:35], v[210:213], 0
	v_mfma_f32_16x16x32_bf16 v[72:75], v[210:213], v[44:47], 0
	s_waitcnt lgkmcnt(6)
	v_mfma_f32_16x16x32_bf16 v[76:79], v[12:15], v[214:217], v[76:79]
	v_mfma_f32_16x16x32_bf16 v[72:75], v[214:217], v[28:31], v[72:75]
	s_waitcnt lgkmcnt(5)
	v_mfma_f32_16x16x32_bf16 v[196:199], v[32:35], v[220:223], 0
	v_mfma_f32_16x16x32_bf16 v[192:195], v[220:223], v[44:47], 0
	s_waitcnt lgkmcnt(4)
	v_mfma_f32_16x16x32_bf16 v[196:199], v[12:15], v[224:227], v[196:199]
	v_mfma_f32_16x16x32_bf16 v[192:195], v[224:227], v[28:31], v[192:195]
	s_waitcnt lgkmcnt(3)
	v_mfma_f32_16x16x32_bf16 v[76:79], v[16:19], v[230:233], v[76:79]
	v_mfma_f32_16x16x32_bf16 v[72:75], v[230:233], v[24:27], v[72:75]
	s_waitcnt lgkmcnt(2)
	v_mfma_f32_16x16x32_bf16 v[196:199], v[16:19], v[234:237], v[196:199]
	v_mfma_f32_16x16x32_bf16 v[192:195], v[234:237], v[24:27], v[192:195]
	s_waitcnt lgkmcnt(1)
	v_mfma_f32_16x16x32_bf16 v[204:207], v[0:3], v[238:241], v[76:79]
	s_nop 2
	s_waitcnt lgkmcnt(0)
	v_mfma_f32_16x16x32_bf16 v[196:199], v[0:3], v[242:245], v[196:199]
	v_mfma_f32_16x16x32_bf16 v[76:79], v[242:245], v[4:7], v[192:195]
	s_nop 2
	v_lshlrev_b32_e32 v193, 16, v188
	v_lshlrev_b32_e32 v192, 16, v186
	v_lshlrev_b32_e32 v195, 16, v89
	v_lshlrev_b32_e32 v194, 16, v185
	v_pk_add_f32 v[192:193], v[192:193], v[204:205] neg_lo:[0,1] neg_hi:[0,1]
	v_pk_add_f32 v[194:195], v[194:195], v[206:207] neg_lo:[0,1] neg_hi:[0,1]
	v_mfma_f32_16x16x32_bf16 v[72:75], v[238:241], v[4:7], v[72:75]
	v_cvt_pk_bf16_f32 v192, v192, v193
	v_cvt_pk_bf16_f32 v193, v194, v195
	ds_write_b64 v182, v[192:193] offset:8704
	s_waitcnt vmcnt(11)
	v_lshlrev_b32_e32 v193, 16, v187
	v_lshlrev_b32_e32 v192, 16, v91
	s_waitcnt vmcnt(9)
	v_lshlrev_b32_e32 v195, 16, v190
	v_lshlrev_b32_e32 v194, 16, v189
	v_pk_add_f32 v[192:193], v[192:193], v[196:197] neg_lo:[0,1] neg_hi:[0,1]
	v_pk_add_f32 v[194:195], v[194:195], v[198:199] neg_lo:[0,1] neg_hi:[0,1]
	v_cvt_pk_bf16_f32 v192, v192, v193
	v_cvt_pk_bf16_f32 v193, v194, v195
	ds_write_b64 v182, v[192:193] offset:11008
	s_cmp_lt_u32 s1, 30
	s_cselect_b64 s[24:25], -1, 0
	s_cmp_gt_u32 s1, 29
	s_cselect_b64 s[22:23], -1, 0
	s_and_b64 vcc, exec, s[22:23]
	s_waitcnt vmcnt(8)
	v_mov_b32_e32 v88, v90
	s_cbranch_vccnz .LBB0_557
	v_add_co_u32_e32 v0, vcc, 0x28000, v144
	s_nop 1
	v_addc_co_u32_e32 v1, vcc, 0, v145, vcc
	v_add_co_u32_e32 v4, vcc, 0x2c000, v144
	s_nop 1
	v_addc_co_u32_e32 v5, vcc, 0, v145, vcc
	v_add_co_u32_e32 v144, vcc, 0x24000, v146
	global_load_dwordx4 v[32:35], v[0:1], off
	global_load_dwordx4 v[12:15], v[0:1], off offset:64
	global_load_dwordx4 v[44:47], v[4:5], off
	global_load_dwordx4 v[28:31], v[4:5], off offset:64
	global_load_dwordx4 v[16:19], v[0:1], off offset:128
	s_nop 0
	global_load_dwordx4 v[0:3], v[0:1], off offset:192
	s_nop 0
	global_load_dwordx4 v[24:27], v[4:5], off offset:128
	s_nop 0
	global_load_dwordx4 v[4:7], v[4:5], off offset:192
	v_addc_co_u32_e32 v145, vcc, 0, v147, vcc
	v_add_co_u32_e32 v146, vcc, 0x24000, v152
	s_nop 1
	v_addc_co_u32_e32 v147, vcc, 0, v153, vcc
	v_add_co_u32_e32 v150, vcc, 0x24000, v150
	s_nop 1
	v_addc_co_u32_e32 v151, vcc, 0, v151, vcc
	v_add_co_u32_e32 v148, vcc, 0x24000, v148
	s_nop 1
	v_addc_co_u32_e32 v149, vcc, 0, v149, vcc
	global_load_ushort v186, v[144:145], off
	global_load_ushort v188, v[144:145], off offset:256
	global_load_ushort v185, v[144:145], off offset:512
	global_load_ushort v89, v[144:145], off offset:768
	global_load_ushort v187, v[146:147], off offset:32
	global_load_ushort v189, v[150:151], off offset:32
	global_load_ushort v190, v[148:149], off offset:32
	global_load_ushort v91, v[144:145], off offset:32
	global_load_dword v88, v113, s[18:19] offset:4

.Lgm_p7_loop:
	ds_read_b128 v[216:219], v132 offset:16384
	ds_read_b128 v[200:203], v133
	ds_read_b128 v[220:223], v132 offset:18432
	ds_read_b128 v[224:227], v132 offset:20480
	ds_read_b128 v[228:231], v132 offset:22528
	ds_read_b128 v[204:207], v133 offset:2048
	ds_read_b128 v[208:211], v133 offset:4096
	ds_read_b128 v[212:215], v133 offset:6144
	s_waitcnt lgkmcnt(3)
	v_mfma_f32_16x16x32_bf16 v[0:3], v[216:219], v[200:203], v[0:3]
	ds_read_b128 v[138:141], v130 offset:16384
	v_mfma_f32_16x16x32_bf16 v[4:7], v[220:223], v[200:203], v[4:7]
	ds_read_b128 v[232:235], v131
	v_mfma_f32_16x16x32_bf16 v[8:11], v[224:227], v[200:203], v[8:11]
	ds_read_b128 v[142:145], v130 offset:18432
	v_mfma_f32_16x16x32_bf16 v[12:15], v[228:231], v[200:203], v[12:15]
	ds_read_b128 v[146:149], v130 offset:20480
	s_waitcnt lgkmcnt(4)
	v_mfma_f32_16x16x32_bf16 v[16:19], v[216:219], v[204:207], v[16:19]
	ds_read_b128 v[150:153], v130 offset:22528
	v_mfma_f32_16x16x32_bf16 v[20:23], v[220:223], v[204:207], v[20:23]
	ds_read_b128 v[236:239], v131 offset:2048
	v_mfma_f32_16x16x32_bf16 v[24:27], v[224:227], v[204:207], v[24:27]
	ds_read_b128 v[240:243], v131 offset:4096
	v_mfma_f32_16x16x32_bf16 v[28:31], v[228:231], v[204:207], v[28:31]
	ds_read_b128 v[244:247], v131 offset:6144
	v_mfma_f32_16x16x32_bf16 v[32:35], v[216:219], v[208:211], v[32:35]
	s_waitcnt vmcnt(8)
	ds_write_b128 v166, v[168:171] offset:32768
	v_mfma_f32_16x16x32_bf16 v[36:39], v[220:223], v[208:211], v[36:39]
	ds_write_b128 v166, v[184:187] offset:49152
	v_mfma_f32_16x16x32_bf16 v[40:43], v[224:227], v[208:211], v[40:43]
	ds_write_b128 v166, v[172:175] offset:36864
	v_mfma_f32_16x16x32_bf16 v[44:47], v[228:231], v[208:211], v[44:47]
	ds_write_b128 v166, v[188:191] offset:53248
	v_mfma_f32_16x16x32_bf16 v[48:51], v[216:219], v[212:215], v[48:51]
	ds_write_b128 v166, v[176:179] offset:40960
	v_mfma_f32_16x16x32_bf16 v[52:55], v[220:223], v[212:215], v[52:55]
	ds_write_b128 v166, v[192:195] offset:57344
	v_mfma_f32_16x16x32_bf16 v[56:59], v[224:227], v[212:215], v[56:59]
	ds_write_b128 v166, v[180:183] offset:45056
	v_mfma_f32_16x16x32_bf16 v[60:63], v[228:231], v[212:215], v[60:63]
	ds_write_b128 v166, v[196:199] offset:61440
	s_waitcnt lgkmcnt(11)
	v_mfma_f32_16x16x32_bf16 v[0:3], v[138:141], v[232:235], v[0:3]
	v_mfma_f32_16x16x32_bf16 v[4:7], v[142:145], v[232:235], v[4:7]
	v_mfma_f32_16x16x32_bf16 v[8:11], v[146:149], v[232:235], v[8:11]
	v_mfma_f32_16x16x32_bf16 v[12:15], v[150:153], v[232:235], v[12:15]
	s_waitcnt lgkmcnt(8)
	v_mfma_f32_16x16x32_bf16 v[16:19], v[138:141], v[236:239], v[16:19]
	s_waitcnt lgkmcnt(0)
	global_load_dwordx4 v[168:171], v126, s[64:65] offset:384
	v_mfma_f32_16x16x32_bf16 v[20:23], v[142:145], v[236:239], v[20:23]
	global_load_dwordx4 v[184:187], v128, s[66:67] offset:384
	v_mfma_f32_16x16x32_bf16 v[24:27], v[146:149], v[236:239], v[24:27]
	global_load_dwordx4 v[172:175], v127, s[64:65] offset:384
	v_mfma_f32_16x16x32_bf16 v[28:31], v[150:153], v[236:239], v[28:31]
	global_load_dwordx4 v[188:191], v129, s[66:67] offset:384
	v_mfma_f32_16x16x32_bf16 v[32:35], v[138:141], v[240:243], v[32:35]
	global_load_dwordx4 v[176:179], v137, s[64:65] offset:384
	v_mfma_f32_16x16x32_bf16 v[36:39], v[142:145], v[240:243], v[36:39]
	global_load_dwordx4 v[192:195], v161, s[66:67] offset:384
	v_mfma_f32_16x16x32_bf16 v[40:43], v[146:149], v[240:243], v[40:43]
	global_load_dwordx4 v[180:183], v117, s[64:65] offset:384
	v_mfma_f32_16x16x32_bf16 v[44:47], v[150:153], v[240:243], v[44:47]
	global_load_dwordx4 v[196:199], v162, s[66:67] offset:384
	v_mfma_f32_16x16x32_bf16 v[48:51], v[138:141], v[244:247], v[48:51]
	v_mfma_f32_16x16x32_bf16 v[52:55], v[142:145], v[244:247], v[52:55]
	v_mfma_f32_16x16x32_bf16 v[56:59], v[146:149], v[244:247], v[56:59]
	v_mfma_f32_16x16x32_bf16 v[60:63], v[150:153], v[244:247], v[60:63]
	s_barrier
	ds_read_b128 v[216:219], v132 offset:49152
	ds_read_b128 v[200:203], v133 offset:32768
	ds_read_b128 v[220:223], v132 offset:51200
	ds_read_b128 v[224:227], v132 offset:53248
	ds_read_b128 v[228:231], v132 offset:55296
	ds_read_b128 v[204:207], v133 offset:34816
	ds_read_b128 v[208:211], v133 offset:36864
	ds_read_b128 v[212:215], v133 offset:38912
	s_waitcnt lgkmcnt(3)
	v_mfma_f32_16x16x32_bf16 v[0:3], v[216:219], v[200:203], v[0:3]
	ds_read_b128 v[138:141], v130 offset:49152
	v_mfma_f32_16x16x32_bf16 v[4:7], v[220:223], v[200:203], v[4:7]
	ds_read_b128 v[232:235], v131 offset:32768
	v_mfma_f32_16x16x32_bf16 v[8:11], v[224:227], v[200:203], v[8:11]
	ds_read_b128 v[142:145], v130 offset:51200
	v_mfma_f32_16x16x32_bf16 v[12:15], v[228:231], v[200:203], v[12:15]
	ds_read_b128 v[146:149], v130 offset:53248
	s_waitcnt lgkmcnt(4)
	v_mfma_f32_16x16x32_bf16 v[16:19], v[216:219], v[204:207], v[16:19]
	ds_read_b128 v[150:153], v130 offset:55296
	v_mfma_f32_16x16x32_bf16 v[20:23], v[220:223], v[204:207], v[20:23]
	ds_read_b128 v[236:239], v131 offset:34816
	v_mfma_f32_16x16x32_bf16 v[24:27], v[224:227], v[204:207], v[24:27]
	ds_read_b128 v[240:243], v131 offset:36864
	v_mfma_f32_16x16x32_bf16 v[28:31], v[228:231], v[204:207], v[28:31]
	ds_read_b128 v[244:247], v131 offset:38912
	v_mfma_f32_16x16x32_bf16 v[32:35], v[216:219], v[208:211], v[32:35]
	s_waitcnt vmcnt(8)
	ds_write_b128 v166, v[64:67]
	v_mfma_f32_16x16x32_bf16 v[36:39], v[220:223], v[208:211], v[36:39]
	ds_write_b128 v166, v[80:83] offset:16384
	v_mfma_f32_16x16x32_bf16 v[40:43], v[224:227], v[208:211], v[40:43]
	ds_write_b128 v166, v[68:71] offset:4096
	v_mfma_f32_16x16x32_bf16 v[44:47], v[228:231], v[208:211], v[44:47]
	ds_write_b128 v166, v[84:87] offset:20480
	v_mfma_f32_16x16x32_bf16 v[48:51], v[216:219], v[212:215], v[48:51]
	ds_write_b128 v166, v[72:75] offset:8192
	v_mfma_f32_16x16x32_bf16 v[52:55], v[220:223], v[212:215], v[52:55]
	ds_write_b128 v166, v[88:91] offset:24576
	v_mfma_f32_16x16x32_bf16 v[56:59], v[224:227], v[212:215], v[56:59]
	ds_write_b128 v166, v[76:79] offset:12288
	v_mfma_f32_16x16x32_bf16 v[60:63], v[228:231], v[212:215], v[60:63]
	ds_write_b128 v166, v[92:95] offset:28672
	s_waitcnt lgkmcnt(11)
	v_mfma_f32_16x16x32_bf16 v[0:3], v[138:141], v[232:235], v[0:3]
	v_mfma_f32_16x16x32_bf16 v[4:7], v[142:145], v[232:235], v[4:7]
	v_mfma_f32_16x16x32_bf16 v[8:11], v[146:149], v[232:235], v[8:11]
	v_mfma_f32_16x16x32_bf16 v[12:15], v[150:153], v[232:235], v[12:15]
	s_waitcnt lgkmcnt(8)
	v_mfma_f32_16x16x32_bf16 v[16:19], v[138:141], v[236:239], v[16:19]
	s_waitcnt lgkmcnt(0)
	global_load_dwordx4 v[64:67], v126, s[64:65] offset:512
	v_mfma_f32_16x16x32_bf16 v[20:23], v[142:145], v[236:239], v[20:23]
	global_load_dwordx4 v[80:83], v128, s[66:67] offset:512
	v_mfma_f32_16x16x32_bf16 v[24:27], v[146:149], v[236:239], v[24:27]
	global_load_dwordx4 v[68:71], v127, s[64:65] offset:512
	v_mfma_f32_16x16x32_bf16 v[28:31], v[150:153], v[236:239], v[28:31]
	global_load_dwordx4 v[84:87], v129, s[66:67] offset:512
	v_mfma_f32_16x16x32_bf16 v[32:35], v[138:141], v[240:243], v[32:35]
	global_load_dwordx4 v[72:75], v137, s[64:65] offset:512
	v_mfma_f32_16x16x32_bf16 v[36:39], v[142:145], v[240:243], v[36:39]
	global_load_dwordx4 v[88:91], v161, s[66:67] offset:512
	v_mfma_f32_16x16x32_bf16 v[40:43], v[146:149], v[240:243], v[40:43]
	global_load_dwordx4 v[76:79], v117, s[64:65] offset:512
	v_mfma_f32_16x16x32_bf16 v[44:47], v[150:153], v[240:243], v[44:47]
	global_load_dwordx4 v[92:95], v162, s[66:67] offset:512
	v_mfma_f32_16x16x32_bf16 v[48:51], v[138:141], v[244:247], v[48:51]
	v_mfma_f32_16x16x32_bf16 v[52:55], v[142:145], v[244:247], v[52:55]
	v_mfma_f32_16x16x32_bf16 v[56:59], v[146:149], v[244:247], v[56:59]
	v_mfma_f32_16x16x32_bf16 v[60:63], v[150:153], v[244:247], v[60:63]
	s_barrier
	s_add_u32 s64, s64, 0x100
	s_addc_u32 s65, s65, 0
	s_add_u32 s66, s66, 0x100
	s_addc_u32 s67, s67, 0
	s_sub_u32 s68, s68, 1
	s_cmp_lg_u32 s68, 0
	s_cbranch_scc1 .Lgm_p7_loop
	ds_read_b128 v[216:219], v132 offset:16384
	ds_read_b128 v[200:203], v133
	ds_read_b128 v[220:223], v132 offset:18432
	ds_read_b128 v[224:227], v132 offset:20480
	ds_read_b128 v[228:231], v132 offset:22528
	ds_read_b128 v[204:207], v133 offset:2048
	ds_read_b128 v[208:211], v133 offset:4096
	ds_read_b128 v[212:215], v133 offset:6144
	s_waitcnt lgkmcnt(3)
	v_mfma_f32_16x16x32_bf16 v[0:3], v[216:219], v[200:203], v[0:3]
	ds_read_b128 v[138:141], v130 offset:16384
	v_mfma_f32_16x16x32_bf16 v[4:7], v[220:223], v[200:203], v[4:7]
	ds_read_b128 v[232:235], v131
	v_mfma_f32_16x16x32_bf16 v[8:11], v[224:227], v[200:203], v[8:11]
	ds_read_b128 v[142:145], v130 offset:18432
	v_mfma_f32_16x16x32_bf16 v[12:15], v[228:231], v[200:203], v[12:15]
	ds_read_b128 v[146:149], v130 offset:20480
	s_waitcnt lgkmcnt(4)
	v_mfma_f32_16x16x32_bf16 v[16:19], v[216:219], v[204:207], v[16:19]
	ds_read_b128 v[150:153], v130 offset:22528
	v_mfma_f32_16x16x32_bf16 v[20:23], v[220:223], v[204:207], v[20:23]
	ds_read_b128 v[236:239], v131 offset:2048
	v_mfma_f32_16x16x32_bf16 v[24:27], v[224:227], v[204:207], v[24:27]
	ds_read_b128 v[240:243], v131 offset:4096
	v_mfma_f32_16x16x32_bf16 v[28:31], v[228:231], v[204:207], v[28:31]
	ds_read_b128 v[244:247], v131 offset:6144
	v_mfma_f32_16x16x32_bf16 v[32:35], v[216:219], v[208:211], v[32:35]
	s_waitcnt vmcnt(8)
	ds_write_b128 v166, v[168:171] offset:32768
	v_mfma_f32_16x16x32_bf16 v[36:39], v[220:223], v[208:211], v[36:39]
	ds_write_b128 v166, v[184:187] offset:49152
	v_mfma_f32_16x16x32_bf16 v[40:43], v[224:227], v[208:211], v[40:43]
	ds_write_b128 v166, v[172:175] offset:36864
	v_mfma_f32_16x16x32_bf16 v[44:47], v[228:231], v[208:211], v[44:47]
	ds_write_b128 v166, v[188:191] offset:53248
	v_mfma_f32_16x16x32_bf16 v[48:51], v[216:219], v[212:215], v[48:51]
	ds_write_b128 v166, v[176:179] offset:40960
	v_mfma_f32_16x16x32_bf16 v[52:55], v[220:223], v[212:215], v[52:55]
	ds_write_b128 v166, v[192:195] offset:57344
	v_mfma_f32_16x16x32_bf16 v[56:59], v[224:227], v[212:215], v[56:59]
	ds_write_b128 v166, v[180:183] offset:45056
	v_mfma_f32_16x16x32_bf16 v[60:63], v[228:231], v[212:215], v[60:63]
	ds_write_b128 v166, v[196:199] offset:61440
	s_waitcnt lgkmcnt(11)
	v_mfma_f32_16x16x32_bf16 v[0:3], v[138:141], v[232:235], v[0:3]
	v_mfma_f32_16x16x32_bf16 v[4:7], v[142:145], v[232:235], v[4:7]
	v_mfma_f32_16x16x32_bf16 v[8:11], v[146:149], v[232:235], v[8:11]
	v_mfma_f32_16x16x32_bf16 v[12:15], v[150:153], v[232:235], v[12:15]
	s_waitcnt lgkmcnt(8)
	v_mfma_f32_16x16x32_bf16 v[16:19], v[138:141], v[236:239], v[16:19]
	s_waitcnt lgkmcnt(0)
	global_load_dwordx4 v[168:171], v126, s[64:65] offset:384
	v_mfma_f32_16x16x32_bf16 v[20:23], v[142:145], v[236:239], v[20:23]
	global_load_dwordx4 v[184:187], v128, s[66:67] offset:384
	v_mfma_f32_16x16x32_bf16 v[24:27], v[146:149], v[236:239], v[24:27]
	global_load_dwordx4 v[172:175], v127, s[64:65] offset:384
	v_mfma_f32_16x16x32_bf16 v[28:31], v[150:153], v[236:239], v[28:31]
	global_load_dwordx4 v[188:191], v129, s[66:67] offset:384
	v_mfma_f32_16x16x32_bf16 v[32:35], v[138:141], v[240:243], v[32:35]
	global_load_dwordx4 v[176:179], v137, s[64:65] offset:384
	v_mfma_f32_16x16x32_bf16 v[36:39], v[142:145], v[240:243], v[36:39]
	global_load_dwordx4 v[192:195], v161, s[66:67] offset:384
	v_mfma_f32_16x16x32_bf16 v[40:43], v[146:149], v[240:243], v[40:43]
	global_load_dwordx4 v[180:183], v117, s[64:65] offset:384
	v_mfma_f32_16x16x32_bf16 v[44:47], v[150:153], v[240:243], v[44:47]
	global_load_dwordx4 v[196:199], v162, s[66:67] offset:384
	v_mfma_f32_16x16x32_bf16 v[48:51], v[138:141], v[244:247], v[48:51]
	v_mfma_f32_16x16x32_bf16 v[52:55], v[142:145], v[244:247], v[52:55]
	v_mfma_f32_16x16x32_bf16 v[56:59], v[146:149], v[244:247], v[56:59]
	v_mfma_f32_16x16x32_bf16 v[60:63], v[150:153], v[244:247], v[60:63]
	s_barrier
	ds_read_b128 v[216:219], v132 offset:49152
	ds_read_b128 v[200:203], v133 offset:32768
	ds_read_b128 v[220:223], v132 offset:51200
	ds_read_b128 v[224:227], v132 offset:53248
	ds_read_b128 v[228:231], v132 offset:55296
	ds_read_b128 v[204:207], v133 offset:34816
	ds_read_b128 v[208:211], v133 offset:36864
	ds_read_b128 v[212:215], v133 offset:38912
	s_waitcnt lgkmcnt(3)
	v_mfma_f32_16x16x32_bf16 v[0:3], v[216:219], v[200:203], v[0:3]
	ds_read_b128 v[138:141], v130 offset:49152
	v_mfma_f32_16x16x32_bf16 v[4:7], v[220:223], v[200:203], v[4:7]
	ds_read_b128 v[232:235], v131 offset:32768
	v_mfma_f32_16x16x32_bf16 v[8:11], v[224:227], v[200:203], v[8:11]
	ds_read_b128 v[142:145], v130 offset:51200
	v_mfma_f32_16x16x32_bf16 v[12:15], v[228:231], v[200:203], v[12:15]
	ds_read_b128 v[146:149], v130 offset:53248
	s_waitcnt lgkmcnt(4)
	v_mfma_f32_16x16x32_bf16 v[16:19], v[216:219], v[204:207], v[16:19]
	ds_read_b128 v[150:153], v130 offset:55296
	v_mfma_f32_16x16x32_bf16 v[20:23], v[220:223], v[204:207], v[20:23]
	ds_read_b128 v[236:239], v131 offset:34816
	v_mfma_f32_16x16x32_bf16 v[24:27], v[224:227], v[204:207], v[24:27]
	ds_read_b128 v[240:243], v131 offset:36864
	v_mfma_f32_16x16x32_bf16 v[28:31], v[228:231], v[204:207], v[28:31]
	ds_read_b128 v[244:247], v131 offset:38912
	v_mfma_f32_16x16x32_bf16 v[32:35], v[216:219], v[208:211], v[32:35]
	s_waitcnt vmcnt(8)
	ds_write_b128 v166, v[64:67]
	v_mfma_f32_16x16x32_bf16 v[36:39], v[220:223], v[208:211], v[36:39]
	ds_write_b128 v166, v[80:83] offset:16384
	v_mfma_f32_16x16x32_bf16 v[40:43], v[224:227], v[208:211], v[40:43]
	ds_write_b128 v166, v[68:71] offset:4096
	v_mfma_f32_16x16x32_bf16 v[44:47], v[228:231], v[208:211], v[44:47]
	ds_write_b128 v166, v[84:87] offset:20480
	v_mfma_f32_16x16x32_bf16 v[48:51], v[216:219], v[212:215], v[48:51]
	ds_write_b128 v166, v[72:75] offset:8192
	v_mfma_f32_16x16x32_bf16 v[52:55], v[220:223], v[212:215], v[52:55]
	ds_write_b128 v166, v[88:91] offset:24576
	v_mfma_f32_16x16x32_bf16 v[56:59], v[224:227], v[212:215], v[56:59]
	ds_write_b128 v166, v[76:79] offset:12288
	v_mfma_f32_16x16x32_bf16 v[60:63], v[228:231], v[212:215], v[60:63]
	ds_write_b128 v166, v[92:95] offset:28672
	s_waitcnt lgkmcnt(11)
	v_mfma_f32_16x16x32_bf16 v[0:3], v[138:141], v[232:235], v[0:3]
	v_mfma_f32_16x16x32_bf16 v[4:7], v[142:145], v[232:235], v[4:7]
	v_mfma_f32_16x16x32_bf16 v[8:11], v[146:149], v[232:235], v[8:11]
	v_mfma_f32_16x16x32_bf16 v[12:15], v[150:153], v[232:235], v[12:15]
	s_waitcnt lgkmcnt(8)
	v_mfma_f32_16x16x32_bf16 v[16:19], v[138:141], v[236:239], v[16:19]
	v_mfma_f32_16x16x32_bf16 v[20:23], v[142:145], v[236:239], v[20:23]
	v_mfma_f32_16x16x32_bf16 v[24:27], v[146:149], v[236:239], v[24:27]
	v_mfma_f32_16x16x32_bf16 v[28:31], v[150:153], v[236:239], v[28:31]
	v_mfma_f32_16x16x32_bf16 v[32:35], v[138:141], v[240:243], v[32:35]
	v_mfma_f32_16x16x32_bf16 v[36:39], v[142:145], v[240:243], v[36:39]
	v_mfma_f32_16x16x32_bf16 v[40:43], v[146:149], v[240:243], v[40:43]
	v_mfma_f32_16x16x32_bf16 v[44:47], v[150:153], v[240:243], v[44:47]
	v_mfma_f32_16x16x32_bf16 v[48:51], v[138:141], v[244:247], v[48:51]
	v_mfma_f32_16x16x32_bf16 v[52:55], v[142:145], v[244:247], v[52:55]
	v_mfma_f32_16x16x32_bf16 v[56:59], v[146:149], v[244:247], v[56:59]
	v_mfma_f32_16x16x32_bf16 v[60:63], v[150:153], v[244:247], v[60:63]
	s_waitcnt lgkmcnt(0)
	s_barrier
	ds_read_b128 v[216:219], v132 offset:16384
	ds_read_b128 v[200:203], v133
	ds_read_b128 v[220:223], v132 offset:18432
	ds_read_b128 v[224:227], v132 offset:20480
	ds_read_b128 v[228:231], v132 offset:22528
	ds_read_b128 v[204:207], v133 offset:2048
	ds_read_b128 v[208:211], v133 offset:4096
	ds_read_b128 v[212:215], v133 offset:6144
	s_waitcnt lgkmcnt(3)
	v_mfma_f32_16x16x32_bf16 v[0:3], v[216:219], v[200:203], v[0:3]
	ds_read_b128 v[138:141], v130 offset:16384
	v_mfma_f32_16x16x32_bf16 v[4:7], v[220:223], v[200:203], v[4:7]
	ds_read_b128 v[232:235], v131
	v_mfma_f32_16x16x32_bf16 v[8:11], v[224:227], v[200:203], v[8:11]
	ds_read_b128 v[142:145], v130 offset:18432
	v_mfma_f32_16x16x32_bf16 v[12:15], v[228:231], v[200:203], v[12:15]
	ds_read_b128 v[146:149], v130 offset:20480
	s_waitcnt lgkmcnt(4)
	v_mfma_f32_16x16x32_bf16 v[16:19], v[216:219], v[204:207], v[16:19]
	ds_read_b128 v[150:153], v130 offset:22528
	v_mfma_f32_16x16x32_bf16 v[20:23], v[220:223], v[204:207], v[20:23]
	ds_read_b128 v[236:239], v131 offset:2048
	v_mfma_f32_16x16x32_bf16 v[24:27], v[224:227], v[204:207], v[24:27]
	ds_read_b128 v[240:243], v131 offset:4096
	v_mfma_f32_16x16x32_bf16 v[28:31], v[228:231], v[204:207], v[28:31]
	ds_read_b128 v[244:247], v131 offset:6144
	v_mfma_f32_16x16x32_bf16 v[32:35], v[216:219], v[208:211], v[32:35]
	s_waitcnt vmcnt(0)
	ds_write_b128 v166, v[168:171] offset:32768
	v_mfma_f32_16x16x32_bf16 v[36:39], v[220:223], v[208:211], v[36:39]
	ds_write_b128 v166, v[184:187] offset:49152
	v_mfma_f32_16x16x32_bf16 v[40:43], v[224:227], v[208:211], v[40:43]
	ds_write_b128 v166, v[172:175] offset:36864
	v_mfma_f32_16x16x32_bf16 v[44:47], v[228:231], v[208:211], v[44:47]
	ds_write_b128 v166, v[188:191] offset:53248
	v_mfma_f32_16x16x32_bf16 v[48:51], v[216:219], v[212:215], v[48:51]
	ds_write_b128 v166, v[176:179] offset:40960
	v_mfma_f32_16x16x32_bf16 v[52:55], v[220:223], v[212:215], v[52:55]
	ds_write_b128 v166, v[192:195] offset:57344
	v_mfma_f32_16x16x32_bf16 v[56:59], v[224:227], v[212:215], v[56:59]
	ds_write_b128 v166, v[180:183] offset:45056
	v_mfma_f32_16x16x32_bf16 v[60:63], v[228:231], v[212:215], v[60:63]
	ds_write_b128 v166, v[196:199] offset:61440
	s_waitcnt lgkmcnt(11)
	v_mfma_f32_16x16x32_bf16 v[0:3], v[138:141], v[232:235], v[0:3]
	v_mfma_f32_16x16x32_bf16 v[4:7], v[142:145], v[232:235], v[4:7]
	v_mfma_f32_16x16x32_bf16 v[8:11], v[146:149], v[232:235], v[8:11]
	v_mfma_f32_16x16x32_bf16 v[12:15], v[150:153], v[232:235], v[12:15]
	s_waitcnt lgkmcnt(8)
	v_mfma_f32_16x16x32_bf16 v[16:19], v[138:141], v[236:239], v[16:19]
	v_mfma_f32_16x16x32_bf16 v[20:23], v[142:145], v[236:239], v[20:23]
	v_mfma_f32_16x16x32_bf16 v[24:27], v[146:149], v[236:239], v[24:27]
	v_mfma_f32_16x16x32_bf16 v[28:31], v[150:153], v[236:239], v[28:31]
	v_mfma_f32_16x16x32_bf16 v[32:35], v[138:141], v[240:243], v[32:35]
	v_mfma_f32_16x16x32_bf16 v[36:39], v[142:145], v[240:243], v[36:39]
	v_mfma_f32_16x16x32_bf16 v[40:43], v[146:149], v[240:243], v[40:43]
	v_mfma_f32_16x16x32_bf16 v[44:47], v[150:153], v[240:243], v[44:47]
	v_mfma_f32_16x16x32_bf16 v[48:51], v[138:141], v[244:247], v[48:51]
	v_mfma_f32_16x16x32_bf16 v[52:55], v[142:145], v[244:247], v[52:55]
	v_mfma_f32_16x16x32_bf16 v[56:59], v[146:149], v[244:247], v[56:59]
	v_mfma_f32_16x16x32_bf16 v[60:63], v[150:153], v[244:247], v[60:63]
	s_waitcnt lgkmcnt(0)
	s_barrier
	ds_read_b128 v[216:219], v132 offset:49152
	ds_read_b128 v[200:203], v133 offset:32768
	ds_read_b128 v[220:223], v132 offset:51200
	ds_read_b128 v[224:227], v132 offset:53248
	ds_read_b128 v[228:231], v132 offset:55296
	ds_read_b128 v[204:207], v133 offset:34816
	ds_read_b128 v[208:211], v133 offset:36864
	ds_read_b128 v[212:215], v133 offset:38912
	s_waitcnt lgkmcnt(3)
	v_mfma_f32_16x16x32_bf16 v[0:3], v[216:219], v[200:203], v[0:3]
	ds_read_b128 v[138:141], v130 offset:49152
	v_mfma_f32_16x16x32_bf16 v[4:7], v[220:223], v[200:203], v[4:7]
	ds_read_b128 v[232:235], v131 offset:32768
	v_mfma_f32_16x16x32_bf16 v[8:11], v[224:227], v[200:203], v[8:11]
	ds_read_b128 v[142:145], v130 offset:51200
	v_mfma_f32_16x16x32_bf16 v[12:15], v[228:231], v[200:203], v[12:15]
	ds_read_b128 v[146:149], v130 offset:53248
	s_waitcnt lgkmcnt(4)
	v_mfma_f32_16x16x32_bf16 v[16:19], v[216:219], v[204:207], v[16:19]
	ds_read_b128 v[150:153], v130 offset:55296
	v_mfma_f32_16x16x32_bf16 v[20:23], v[220:223], v[204:207], v[20:23]
	ds_read_b128 v[236:239], v131 offset:34816
	v_mfma_f32_16x16x32_bf16 v[24:27], v[224:227], v[204:207], v[24:27]
	ds_read_b128 v[240:243], v131 offset:36864
	v_mfma_f32_16x16x32_bf16 v[28:31], v[228:231], v[204:207], v[28:31]
	ds_read_b128 v[244:247], v131 offset:38912
	v_mfma_f32_16x16x32_bf16 v[32:35], v[216:219], v[208:211], v[32:35]
	v_mfma_f32_16x16x32_bf16 v[36:39], v[220:223], v[208:211], v[36:39]
	v_mfma_f32_16x16x32_bf16 v[40:43], v[224:227], v[208:211], v[40:43]
	v_mfma_f32_16x16x32_bf16 v[44:47], v[228:231], v[208:211], v[44:47]
	v_mfma_f32_16x16x32_bf16 v[48:51], v[216:219], v[212:215], v[48:51]
	v_mfma_f32_16x16x32_bf16 v[52:55], v[220:223], v[212:215], v[52:55]
	v_mfma_f32_16x16x32_bf16 v[56:59], v[224:227], v[212:215], v[56:59]
	v_mfma_f32_16x16x32_bf16 v[60:63], v[228:231], v[212:215], v[60:63]
	s_waitcnt lgkmcnt(3)
	v_mfma_f32_16x16x32_bf16 v[0:3], v[138:141], v[232:235], v[0:3]
	v_mfma_f32_16x16x32_bf16 v[4:7], v[142:145], v[232:235], v[4:7]
	v_mfma_f32_16x16x32_bf16 v[8:11], v[146:149], v[232:235], v[8:11]
	v_mfma_f32_16x16x32_bf16 v[12:15], v[150:153], v[232:235], v[12:15]
	s_waitcnt lgkmcnt(0)
	v_mfma_f32_16x16x32_bf16 v[16:19], v[138:141], v[236:239], v[16:19]
	v_mfma_f32_16x16x32_bf16 v[20:23], v[142:145], v[236:239], v[20:23]
	v_mfma_f32_16x16x32_bf16 v[24:27], v[146:149], v[236:239], v[24:27]
	v_mfma_f32_16x16x32_bf16 v[28:31], v[150:153], v[236:239], v[28:31]
	v_mfma_f32_16x16x32_bf16 v[32:35], v[138:141], v[240:243], v[32:35]
	v_mfma_f32_16x16x32_bf16 v[36:39], v[142:145], v[240:243], v[36:39]
	v_mfma_f32_16x16x32_bf16 v[40:43], v[146:149], v[240:243], v[40:43]
	v_mfma_f32_16x16x32_bf16 v[44:47], v[150:153], v[240:243], v[44:47]
	v_mfma_f32_16x16x32_bf16 v[48:51], v[138:141], v[244:247], v[48:51]
	v_mfma_f32_16x16x32_bf16 v[52:55], v[142:145], v[244:247], v[52:55]
	v_mfma_f32_16x16x32_bf16 v[56:59], v[146:149], v[244:247], v[56:59]
	v_mfma_f32_16x16x32_bf16 v[60:63], v[150:153], v[244:247], v[60:63]
	s_nop 7
	s_barrier
	ds_write_b128 v136, v[0:3]
	ds_write_b128 v136, v[4:7] offset:64
	ds_write_b128 v136, v[8:11] offset:128
	ds_write_b128 v136, v[12:15] offset:192
	ds_write_b128 v136, v[16:19] offset:8448
	ds_write_b128 v136, v[20:23] offset:8512
	ds_write_b128 v136, v[24:27] offset:8576
	ds_write_b128 v136, v[28:31] offset:8640
	ds_write_b128 v136, v[32:35] offset:16896
	ds_write_b128 v136, v[36:39] offset:16960
	ds_write_b128 v136, v[40:43] offset:17024
	ds_write_b128 v136, v[44:47] offset:17088
	ds_write_b128 v136, v[48:51] offset:25344
	ds_write_b128 v136, v[52:55] offset:25408
	ds_write_b128 v136, v[56:59] offset:25472
	ds_write_b128 v136, v[60:63] offset:25536
	v_lshl_or_b32 v20, s62, 6, v107
	v_ashrrev_i32_e32 v21, 31, v20
	v_lshlrev_b64 v[22:23], 2, v[20:21]
	v_lshl_add_u64 v[0:1], s[82:83], 0, v[22:23]
	v_lshl_add_u64 v[16:17], s[28:29], 0, v[22:23]
	v_lshl_add_u64 v[18:19], s[30:31], 0, v[22:23]
	s_waitcnt lgkmcnt(0)
	s_barrier
	v_lshl_add_u64 v[2:3], s[18:19], 0, v[22:23]
	v_lshl_add_u64 v[4:5], s[22:23], 0, v[22:23]
	v_lshl_add_u64 v[6:7], s[26:27], 0, v[22:23]
	global_load_dwordx2 v[8:9], v[0:1], off
	global_load_dwordx2 v[10:11], v[2:3], off
	global_load_dwordx2 v[12:13], v[4:5], off
	global_load_dwordx2 v[14:15], v[6:7], off
	s_nop 0
	global_load_dwordx2 v[16:17], v[16:17], off
	s_nop 0
	global_load_dwordx2 v[18:19], v[18:19], off
	s_mov_b64 s[4:5], -1
	s_and_b64 vcc, exec, s[36:37]
	s_cbranch_vccz .LBB0_852
	s_mul_i32 s65, s34, 17
	s_sub_i32 s64, s61, s65
	s_cmp_lt_i32 s64, 1
	s_cbranch_scc1 .Lp7epi_slow
	s_cmp_gt_i32 s64, 15
	s_cbranch_scc1 .Lp7epi_slow
	v_add_u32_e32 v127, 0x840, v134
	v_add_u32_e32 v128, 0x1080, v134
	v_add_u32_e32 v129, 0x18c0, v134
	s_mov_b64 s[70:71], exec
	s_and_b64 exec, exec, s[0:1]
	ds_read2_b64 v[232:235], v111 offset1:16
	ds_read2_b64 v[236:239], v113 offset1:16
	s_mov_b64 exec, s[70:71]
	ds_read2_b64 v[168:171], v134 offset0:0 offset1:16
	ds_read2_b64 v[172:175], v134 offset0:66 offset1:82
	ds_read2_b64 v[176:179], v134 offset0:132 offset1:148
	ds_read2_b64 v[180:183], v134 offset0:198 offset1:214
	ds_read2_b64 v[184:187], v127 offset0:0 offset1:16
	ds_read2_b64 v[188:191], v127 offset0:66 offset1:82
	ds_read2_b64 v[192:195], v127 offset0:132 offset1:148
	ds_read2_b64 v[196:199], v127 offset0:198 offset1:214
	ds_read2_b64 v[200:203], v128 offset0:0 offset1:16
	ds_read2_b64 v[204:207], v128 offset0:66 offset1:82
	ds_read2_b64 v[208:211], v128 offset0:132 offset1:148
	ds_read2_b64 v[212:215], v128 offset0:198 offset1:214
	ds_read2_b64 v[216:219], v129 offset0:0 offset1:16
	s_waitcnt lgkmcnt(8)
	ds_read2_b64 v[220:223], v129 offset0:66 offset1:82
	ds_read2_b64 v[224:227], v129 offset0:132 offset1:148
	ds_read2_b64 v[228:231], v129 offset0:198 offset1:214
	s_lshl_b32 s65, s34, 11
	s_mul_i32 s72, s64, 0x7e
	s_add_i32 s65, s65, s72
	s_add_i32 s65, s65, -2
	s_mul_i32 s65, s65, 0x1600
	s_add_u32 s66, s80, s65
	s_addc_u32 s67, s81, 0
	v_mul_u32_u24_e32 v126, 0x1600, v105
	v_lshl_add_u32 v126, v20, 1, v126
	s_waitcnt vmcnt(0)
	v_mul_f32_e32 v40, v8, v232
	v_mul_f32_e32 v48, v8, v236
	v_mul_f32_e32 v56, v8, v168
	v_mul_f32_e32 v64, v8, v172
	v_mul_f32_e32 v41, v9, v233
	v_mul_f32_e32 v49, v9, v237
	v_mul_f32_e32 v57, v9, v169
	v_mul_f32_e32 v65, v9, v173
	v_mul_f32_e32 v42, v14, v234
	v_mul_f32_e32 v50, v14, v238
	v_mul_f32_e32 v58, v14, v170
	v_mul_f32_e32 v66, v14, v174
	v_mul_f32_e32 v43, v15, v235
	v_mul_f32_e32 v51, v15, v239
	v_mul_f32_e32 v59, v15, v171
	v_mul_f32_e32 v67, v15, v175
	v_fma_f32 v40, v10, v236, v40
	v_fma_f32 v48, v10, v168, v48
	v_fma_f32 v56, v10, v172, v56
	v_fma_f32 v64, v10, v176, v64
	v_fma_f32 v41, v11, v237, v41
	v_fma_f32 v49, v11, v169, v49
	v_fma_f32 v57, v11, v173, v57
	v_fma_f32 v65, v11, v177, v65
	v_fma_f32 v42, v16, v238, v42
	v_fma_f32 v50, v16, v170, v50
	v_fma_f32 v58, v16, v174, v58
	v_fma_f32 v66, v16, v178, v66
	v_fma_f32 v43, v17, v239, v43
	v_fma_f32 v51, v17, v171, v51
	v_fma_f32 v59, v17, v175, v59
	v_fma_f32 v67, v17, v179, v67
	v_fma_f32 v40, v12, v168, v40
	v_fma_f32 v48, v12, v172, v48
	v_fma_f32 v56, v12, v176, v56
	v_fma_f32 v64, v12, v180, v64
	v_fma_f32 v41, v13, v169, v41
	v_fma_f32 v49, v13, v173, v49
	v_fma_f32 v57, v13, v177, v57
	v_fma_f32 v65, v13, v181, v65
	v_fma_f32 v42, v18, v170, v42
	v_fma_f32 v50, v18, v174, v50
	v_fma_f32 v58, v18, v178, v58
	v_fma_f32 v66, v18, v182, v66
	v_fma_f32 v43, v19, v171, v43
	v_fma_f32 v51, v19, v175, v51
	v_fma_f32 v59, v19, v179, v59
	v_fma_f32 v67, v19, v183, v67
	v_mul_f32_e32 v44, 0xbfb8aa3b, v40
	v_mul_f32_e32 v52, 0xbfb8aa3b, v48
	v_mul_f32_e32 v60, 0xbfb8aa3b, v56
	v_mul_f32_e32 v68, 0xbfb8aa3b, v64
	v_mul_f32_e32 v45, 0xbfb8aa3b, v41
	v_mul_f32_e32 v53, 0xbfb8aa3b, v49
	v_mul_f32_e32 v61, 0xbfb8aa3b, v57
	v_mul_f32_e32 v69, 0xbfb8aa3b, v65
	v_exp_f32_e32 v44, v44
	v_exp_f32_e32 v52, v52
	v_exp_f32_e32 v60, v60
	v_exp_f32_e32 v68, v68
	v_exp_f32_e32 v45, v45
	v_exp_f32_e32 v53, v53
	v_exp_f32_e32 v61, v61
	v_exp_f32_e32 v69, v69
	v_add_f32_e32 v44, 1.0, v44
	v_add_f32_e32 v52, 1.0, v52
	v_add_f32_e32 v60, 1.0, v60
	v_add_f32_e32 v68, 1.0, v68
	v_add_f32_e32 v45, 1.0, v45
	v_add_f32_e32 v53, 1.0, v53
	v_add_f32_e32 v61, 1.0, v61
	v_add_f32_e32 v69, 1.0, v69
	v_rcp_f32_e32 v44, v44
	v_rcp_f32_e32 v52, v52
	v_rcp_f32_e32 v60, v60
	v_rcp_f32_e32 v68, v68
	v_rcp_f32_e32 v45, v45
	v_rcp_f32_e32 v53, v53
	v_rcp_f32_e32 v61, v61
	v_rcp_f32_e32 v69, v69
	v_mul_f32_e32 v40, v40, v44
	v_mul_f32_e32 v48, v48, v52
	v_mul_f32_e32 v56, v56, v60
	v_mul_f32_e32 v64, v64, v68
	v_mul_f32_e32 v41, v41, v45
	v_mul_f32_e32 v49, v49, v53
	v_mul_f32_e32 v57, v57, v61
	v_mul_f32_e32 v65, v65, v69
	v_mul_f32_e32 v40, v42, v40
	v_mul_f32_e32 v48, v50, v48
	v_mul_f32_e32 v56, v58, v56
	v_mul_f32_e32 v64, v66, v64
	v_mul_f32_e32 v41, v43, v41
	v_mul_f32_e32 v49, v51, v49
	v_mul_f32_e32 v57, v59, v57
	v_mul_f32_e32 v65, v67, v65
	v_cvt_pk_bf16_f32 v80, v40, v41
	v_cvt_pk_bf16_f32 v81, v48, v49
	v_cvt_pk_bf16_f32 v82, v56, v57
	v_cvt_pk_bf16_f32 v83, v64, v65
	s_waitcnt lgkmcnt(10)
	s_waitcnt lgkmcnt(9)
	s_waitcnt lgkmcnt(8)
	v_mul_f32_e32 v40, v8, v176
	v_mul_f32_e32 v48, v8, v180
	v_mul_f32_e32 v56, v8, v184
	v_mul_f32_e32 v64, v8, v188
	v_mul_f32_e32 v41, v9, v177
	v_mul_f32_e32 v49, v9, v181
	v_mul_f32_e32 v57, v9, v185
	v_mul_f32_e32 v65, v9, v189
	v_mul_f32_e32 v42, v14, v178
	v_mul_f32_e32 v50, v14, v182
	v_mul_f32_e32 v58, v14, v186
	v_mul_f32_e32 v66, v14, v190
	v_mul_f32_e32 v43, v15, v179
	v_mul_f32_e32 v51, v15, v183
	v_mul_f32_e32 v59, v15, v187
	v_mul_f32_e32 v67, v15, v191
	v_fma_f32 v40, v10, v180, v40
	v_fma_f32 v48, v10, v184, v48
	v_fma_f32 v56, v10, v188, v56
	v_fma_f32 v64, v10, v192, v64
	v_fma_f32 v41, v11, v181, v41
	v_fma_f32 v49, v11, v185, v49
	v_fma_f32 v57, v11, v189, v57
	v_fma_f32 v65, v11, v193, v65
	v_fma_f32 v42, v16, v182, v42
	v_fma_f32 v50, v16, v186, v50
	v_fma_f32 v58, v16, v190, v58
	v_fma_f32 v66, v16, v194, v66
	v_fma_f32 v43, v17, v183, v43
	v_fma_f32 v51, v17, v187, v51
	v_fma_f32 v59, v17, v191, v59
	v_fma_f32 v67, v17, v195, v67
	v_fma_f32 v40, v12, v184, v40
	v_fma_f32 v48, v12, v188, v48
	v_fma_f32 v56, v12, v192, v56
	v_fma_f32 v64, v12, v196, v64
	v_fma_f32 v41, v13, v185, v41
	v_fma_f32 v49, v13, v189, v49
	v_fma_f32 v57, v13, v193, v57
	v_fma_f32 v65, v13, v197, v65
	v_fma_f32 v42, v18, v186, v42
	v_fma_f32 v50, v18, v190, v50
	v_fma_f32 v58, v18, v194, v58
	v_fma_f32 v66, v18, v198, v66
	v_fma_f32 v43, v19, v187, v43
	v_fma_f32 v51, v19, v191, v51
	v_fma_f32 v59, v19, v195, v59
	v_fma_f32 v67, v19, v199, v67
	v_mul_f32_e32 v44, 0xbfb8aa3b, v40
	v_mul_f32_e32 v52, 0xbfb8aa3b, v48
	v_mul_f32_e32 v60, 0xbfb8aa3b, v56
	v_mul_f32_e32 v68, 0xbfb8aa3b, v64
	v_mul_f32_e32 v45, 0xbfb8aa3b, v41
	v_mul_f32_e32 v53, 0xbfb8aa3b, v49
	v_mul_f32_e32 v61, 0xbfb8aa3b, v57
	v_mul_f32_e32 v69, 0xbfb8aa3b, v65
	v_exp_f32_e32 v44, v44
	v_exp_f32_e32 v52, v52
	v_exp_f32_e32 v60, v60
	v_exp_f32_e32 v68, v68
	v_exp_f32_e32 v45, v45
	v_exp_f32_e32 v53, v53
	v_exp_f32_e32 v61, v61
	v_exp_f32_e32 v69, v69
	v_add_f32_e32 v44, 1.0, v44
	v_add_f32_e32 v52, 1.0, v52
	v_add_f32_e32 v60, 1.0, v60
	v_add_f32_e32 v68, 1.0, v68
	v_add_f32_e32 v45, 1.0, v45
	v_add_f32_e32 v53, 1.0, v53
	v_add_f32_e32 v61, 1.0, v61
	v_add_f32_e32 v69, 1.0, v69
	v_rcp_f32_e32 v44, v44
	v_rcp_f32_e32 v52, v52
	v_rcp_f32_e32 v60, v60
	v_rcp_f32_e32 v68, v68
	v_rcp_f32_e32 v45, v45
	v_rcp_f32_e32 v53, v53
	v_rcp_f32_e32 v61, v61
	v_rcp_f32_e32 v69, v69
	v_mul_f32_e32 v40, v40, v44
	v_mul_f32_e32 v48, v48, v52
	v_mul_f32_e32 v56, v56, v60
	v_mul_f32_e32 v64, v64, v68
	v_mul_f32_e32 v41, v41, v45
	v_mul_f32_e32 v49, v49, v53
	v_mul_f32_e32 v57, v57, v61
	v_mul_f32_e32 v65, v65, v69
	v_mul_f32_e32 v40, v42, v40
	v_mul_f32_e32 v48, v50, v48
	v_mul_f32_e32 v56, v58, v56
	v_mul_f32_e32 v64, v66, v64
	v_mul_f32_e32 v41, v43, v41
	v_mul_f32_e32 v49, v51, v49
	v_mul_f32_e32 v57, v59, v57
	v_mul_f32_e32 v65, v67, v65
	v_cvt_pk_bf16_f32 v84, v40, v41
	v_cvt_pk_bf16_f32 v85, v48, v49
	v_cvt_pk_bf16_f32 v86, v56, v57
	v_cvt_pk_bf16_f32 v87, v64, v65
	s_waitcnt lgkmcnt(7)
	s_waitcnt lgkmcnt(6)
	s_waitcnt lgkmcnt(5)
	s_waitcnt lgkmcnt(4)
	v_mul_f32_e32 v40, v8, v192
	v_mul_f32_e32 v48, v8, v196
	v_mul_f32_e32 v56, v8, v200
	v_mul_f32_e32 v64, v8, v204
	v_mul_f32_e32 v41, v9, v193
	v_mul_f32_e32 v49, v9, v197
	v_mul_f32_e32 v57, v9, v201
	v_mul_f32_e32 v65, v9, v205
	v_mul_f32_e32 v42, v14, v194
	v_mul_f32_e32 v50, v14, v198
	v_mul_f32_e32 v58, v14, v202
	v_mul_f32_e32 v66, v14, v206
	v_mul_f32_e32 v43, v15, v195
	v_mul_f32_e32 v51, v15, v199
	v_mul_f32_e32 v59, v15, v203
	v_mul_f32_e32 v67, v15, v207
	v_fma_f32 v40, v10, v196, v40
	v_fma_f32 v48, v10, v200, v48
	v_fma_f32 v56, v10, v204, v56
	v_fma_f32 v64, v10, v208, v64
	v_fma_f32 v41, v11, v197, v41
	v_fma_f32 v49, v11, v201, v49
	v_fma_f32 v57, v11, v205, v57
	v_fma_f32 v65, v11, v209, v65
	v_fma_f32 v42, v16, v198, v42
	v_fma_f32 v50, v16, v202, v50
	v_fma_f32 v58, v16, v206, v58
	v_fma_f32 v66, v16, v210, v66
	v_fma_f32 v43, v17, v199, v43
	v_fma_f32 v51, v17, v203, v51
	v_fma_f32 v59, v17, v207, v59
	v_fma_f32 v67, v17, v211, v67
	v_fma_f32 v40, v12, v200, v40
	v_fma_f32 v48, v12, v204, v48
	v_fma_f32 v56, v12, v208, v56
	v_fma_f32 v64, v12, v212, v64
	v_fma_f32 v41, v13, v201, v41
	v_fma_f32 v49, v13, v205, v49
	v_fma_f32 v57, v13, v209, v57
	v_fma_f32 v65, v13, v213, v65
	v_fma_f32 v42, v18, v202, v42
	v_fma_f32 v50, v18, v206, v50
	v_fma_f32 v58, v18, v210, v58
	v_fma_f32 v66, v18, v214, v66
	v_fma_f32 v43, v19, v203, v43
	v_fma_f32 v51, v19, v207, v51
	v_fma_f32 v59, v19, v211, v59
	v_fma_f32 v67, v19, v215, v67
	v_mul_f32_e32 v44, 0xbfb8aa3b, v40
	v_mul_f32_e32 v52, 0xbfb8aa3b, v48
	v_mul_f32_e32 v60, 0xbfb8aa3b, v56
	v_mul_f32_e32 v68, 0xbfb8aa3b, v64
	v_mul_f32_e32 v45, 0xbfb8aa3b, v41
	v_mul_f32_e32 v53, 0xbfb8aa3b, v49
	v_mul_f32_e32 v61, 0xbfb8aa3b, v57
	v_mul_f32_e32 v69, 0xbfb8aa3b, v65
	v_exp_f32_e32 v44, v44
	v_exp_f32_e32 v52, v52
	v_exp_f32_e32 v60, v60
	v_exp_f32_e32 v68, v68
	v_exp_f32_e32 v45, v45
	v_exp_f32_e32 v53, v53
	v_exp_f32_e32 v61, v61
	v_exp_f32_e32 v69, v69
	v_add_f32_e32 v44, 1.0, v44
	v_add_f32_e32 v52, 1.0, v52
	v_add_f32_e32 v60, 1.0, v60
	v_add_f32_e32 v68, 1.0, v68
	v_add_f32_e32 v45, 1.0, v45
	v_add_f32_e32 v53, 1.0, v53
	v_add_f32_e32 v61, 1.0, v61
	v_add_f32_e32 v69, 1.0, v69
	v_rcp_f32_e32 v44, v44
	v_rcp_f32_e32 v52, v52
	v_rcp_f32_e32 v60, v60
	v_rcp_f32_e32 v68, v68
	v_rcp_f32_e32 v45, v45
	v_rcp_f32_e32 v53, v53
	v_rcp_f32_e32 v61, v61
	v_rcp_f32_e32 v69, v69
	v_mul_f32_e32 v40, v40, v44
	v_mul_f32_e32 v48, v48, v52
	v_mul_f32_e32 v56, v56, v60
	v_mul_f32_e32 v64, v64, v68
	v_mul_f32_e32 v41, v41, v45
	v_mul_f32_e32 v49, v49, v53
	v_mul_f32_e32 v57, v57, v61
	v_mul_f32_e32 v65, v65, v69
	v_mul_f32_e32 v40, v42, v40
	v_mul_f32_e32 v48, v50, v48
	v_mul_f32_e32 v56, v58, v56
	v_mul_f32_e32 v64, v66, v64
	v_mul_f32_e32 v41, v43, v41
	v_mul_f32_e32 v49, v51, v49
	v_mul_f32_e32 v57, v59, v57
	v_mul_f32_e32 v65, v67, v65
	v_cvt_pk_bf16_f32 v88, v40, v41
	v_cvt_pk_bf16_f32 v89, v48, v49
	v_cvt_pk_bf16_f32 v90, v56, v57
	v_cvt_pk_bf16_f32 v91, v64, v65
	s_waitcnt lgkmcnt(3)
	s_waitcnt lgkmcnt(2)
	s_waitcnt lgkmcnt(1)
	s_waitcnt lgkmcnt(0)
	v_mul_f32_e32 v40, v8, v208
	v_mul_f32_e32 v48, v8, v212
	v_mul_f32_e32 v56, v8, v216
	v_mul_f32_e32 v64, v8, v220
	v_mul_f32_e32 v41, v9, v209
	v_mul_f32_e32 v49, v9, v213
	v_mul_f32_e32 v57, v9, v217
	v_mul_f32_e32 v65, v9, v221
	v_mul_f32_e32 v42, v14, v210
	v_mul_f32_e32 v50, v14, v214
	v_mul_f32_e32 v58, v14, v218
	v_mul_f32_e32 v66, v14, v222
	v_mul_f32_e32 v43, v15, v211
	v_mul_f32_e32 v51, v15, v215
	v_mul_f32_e32 v59, v15, v219
	v_mul_f32_e32 v67, v15, v223
	v_fma_f32 v40, v10, v212, v40
	v_fma_f32 v48, v10, v216, v48
	v_fma_f32 v56, v10, v220, v56
	v_fma_f32 v64, v10, v224, v64
	v_fma_f32 v41, v11, v213, v41
	v_fma_f32 v49, v11, v217, v49
	v_fma_f32 v57, v11, v221, v57
	v_fma_f32 v65, v11, v225, v65
	v_fma_f32 v42, v16, v214, v42
	v_fma_f32 v50, v16, v218, v50
	v_fma_f32 v58, v16, v222, v58
	v_fma_f32 v66, v16, v226, v66
	v_fma_f32 v43, v17, v215, v43
	v_fma_f32 v51, v17, v219, v51
	v_fma_f32 v59, v17, v223, v59
	v_fma_f32 v67, v17, v227, v67
	v_fma_f32 v40, v12, v216, v40
	v_fma_f32 v48, v12, v220, v48
	v_fma_f32 v56, v12, v224, v56
	v_fma_f32 v64, v12, v228, v64
	v_fma_f32 v41, v13, v217, v41
	v_fma_f32 v49, v13, v221, v49
	v_fma_f32 v57, v13, v225, v57
	v_fma_f32 v65, v13, v229, v65
	v_fma_f32 v42, v18, v218, v42
	v_fma_f32 v50, v18, v222, v50
	v_fma_f32 v58, v18, v226, v58
	v_fma_f32 v66, v18, v230, v66
	v_fma_f32 v43, v19, v219, v43
	v_fma_f32 v51, v19, v223, v51
	v_fma_f32 v59, v19, v227, v59
	v_fma_f32 v67, v19, v231, v67
	v_mul_f32_e32 v44, 0xbfb8aa3b, v40
	v_mul_f32_e32 v52, 0xbfb8aa3b, v48
	v_mul_f32_e32 v60, 0xbfb8aa3b, v56
	v_mul_f32_e32 v68, 0xbfb8aa3b, v64
	v_mul_f32_e32 v45, 0xbfb8aa3b, v41
	v_mul_f32_e32 v53, 0xbfb8aa3b, v49
	v_mul_f32_e32 v61, 0xbfb8aa3b, v57
	v_mul_f32_e32 v69, 0xbfb8aa3b, v65
	v_exp_f32_e32 v44, v44
	v_exp_f32_e32 v52, v52
	v_exp_f32_e32 v60, v60
	v_exp_f32_e32 v68, v68
	v_exp_f32_e32 v45, v45
	v_exp_f32_e32 v53, v53
	v_exp_f32_e32 v61, v61
	v_exp_f32_e32 v69, v69
	v_add_f32_e32 v44, 1.0, v44
	v_add_f32_e32 v52, 1.0, v52
	v_add_f32_e32 v60, 1.0, v60
	v_add_f32_e32 v68, 1.0, v68
	v_add_f32_e32 v45, 1.0, v45
	v_add_f32_e32 v53, 1.0, v53
	v_add_f32_e32 v61, 1.0, v61
	v_add_f32_e32 v69, 1.0, v69
	v_rcp_f32_e32 v44, v44
	v_rcp_f32_e32 v52, v52
	v_rcp_f32_e32 v60, v60
	v_rcp_f32_e32 v68, v68
	v_rcp_f32_e32 v45, v45
	v_rcp_f32_e32 v53, v53
	v_rcp_f32_e32 v61, v61
	v_rcp_f32_e32 v69, v69
	v_mul_f32_e32 v40, v40, v44
	v_mul_f32_e32 v48, v48, v52
	v_mul_f32_e32 v56, v56, v60
	v_mul_f32_e32 v64, v64, v68
	v_mul_f32_e32 v41, v41, v45
	v_mul_f32_e32 v49, v49, v53
	v_mul_f32_e32 v57, v57, v61
	v_mul_f32_e32 v65, v65, v69
	v_mul_f32_e32 v40, v42, v40
	v_mul_f32_e32 v48, v50, v48
	v_mul_f32_e32 v56, v58, v56
	v_mul_f32_e32 v64, v66, v64
	v_mul_f32_e32 v41, v43, v41
	v_mul_f32_e32 v49, v51, v49
	v_mul_f32_e32 v57, v59, v57
	v_mul_f32_e32 v65, v67, v65
	v_cvt_pk_bf16_f32 v92, v40, v41
	v_cvt_pk_bf16_f32 v93, v48, v49
	v_cvt_pk_bf16_f32 v94, v56, v57
	v_cvt_pk_bf16_f32 v95, v64, v65
	s_and_b64 exec, exec, s[0:1]
	global_store_dword v126, v80, s[66:67]
	s_add_u32 s66, s66, 0x1600
	s_addc_u32 s67, s67, 0
	global_store_dword v126, v81, s[66:67]
	s_add_u32 s66, s66, 0x1600
	s_addc_u32 s67, s67, 0
	s_mov_b64 exec, s[70:71]
	global_store_dword v126, v82, s[66:67]
	s_add_u32 s66, s66, 0x1600
	s_addc_u32 s67, s67, 0
	global_store_dword v126, v83, s[66:67]
	s_add_u32 s66, s66, 0x1600
	s_addc_u32 s67, s67, 0
	global_store_dword v126, v84, s[66:67]
	s_add_u32 s66, s66, 0x1600
	s_addc_u32 s67, s67, 0
	global_store_dword v126, v85, s[66:67]
	s_add_u32 s66, s66, 0x1600
	s_addc_u32 s67, s67, 0
	global_store_dword v126, v86, s[66:67]
	s_add_u32 s66, s66, 0x1600
	s_addc_u32 s67, s67, 0
	global_store_dword v126, v87, s[66:67]
	s_add_u32 s66, s66, 0x1600
	s_addc_u32 s67, s67, 0
	global_store_dword v126, v88, s[66:67]
	s_add_u32 s66, s66, 0x1600
	s_addc_u32 s67, s67, 0
	global_store_dword v126, v89, s[66:67]
	s_add_u32 s66, s66, 0x1600
	s_addc_u32 s67, s67, 0
	global_store_dword v126, v90, s[66:67]
	s_add_u32 s66, s66, 0x1600
	s_addc_u32 s67, s67, 0
	global_store_dword v126, v91, s[66:67]
	s_add_u32 s66, s66, 0x1600
	s_addc_u32 s67, s67, 0
	global_store_dword v126, v92, s[66:67]
	s_add_u32 s66, s66, 0x1600
	s_addc_u32 s67, s67, 0
	global_store_dword v126, v93, s[66:67]
	s_add_u32 s66, s66, 0x1600
	s_addc_u32 s67, s67, 0
	global_store_dword v126, v94, s[66:67]
	s_add_u32 s66, s66, 0x1600
	s_addc_u32 s67, s67, 0
	global_store_dword v126, v95, s[66:67]
	s_branch .LBB0_851
.Lp7epi_slow:
	v_mov_b32_e32 v117, v116
	v_mov_b64_e32 v[6:7], v[116:117]
	v_mov_b64_e32 v[2:3], v[116:117]
	v_mov_b64_e32 v[4:5], v[116:117]
	v_mov_b64_e32 v[0:1], v[116:117]
	s_and_saveexec_b64 s[4:5], s[0:1]
	s_cbranch_execz .LBB0_836
	ds_read2_b64 v[0:3], v111 offset1:16
	ds_read2_b64 v[4:7], v113 offset1:16

.LBB0_838:
	ds_read2_b64 v[30:33], v38 offset1:16
	v_add_u32_e32 v26, s10, v37
	v_add_u32_e32 v28, -2, v26
	v_cmp_gt_i32_e32 vcc, 0, v28
	v_cmp_ne_u32_e64 s[4:5], s10, v135
	s_waitcnt lgkmcnt(0)
	v_cndmask_b32_e64 v35, v31, 0, vcc
	v_cndmask_b32_e64 v34, v30, 0, vcc
	v_cndmask_b32_e64 v31, v33, 0, vcc
	v_cndmask_b32_e64 v30, v32, 0, vcc
	v_cmp_gt_i32_e32 vcc, s47, v28
	s_and_b64 s[34:35], s[4:5], vcc
	s_and_saveexec_b64 s[8:9], s[34:35]
	s_cbranch_execz .LBB0_841
	v_pk_mul_f32 v[0:1], v[8:9], v[0:1]
	v_pk_mul_f32 v[2:3], v[14:15], v[2:3]
	v_pk_fma_f32 v[0:1], v[10:11], v[4:5], v[0:1]
	v_pk_fma_f32 v[2:3], v[16:17], v[6:7], v[2:3]
	v_pk_fma_f32 v[0:1], v[12:13], v[34:35], v[0:1]
	v_pk_fma_f32 v[2:3], v[18:19], v[30:31], v[2:3]
	v_mul_f32_e32 v27, 0xbfb8aa3b, v0
	v_exp_f32_e32 v32, v27
	v_mul_f32_e32 v27, 0xbfb8aa3b, v1
	v_exp_f32_e32 v33, v27
	s_nop 0
	v_pk_add_f32 v[32:33], v[32:33], 1.0 op_sel_hi:[1,0]
	s_nop 4
	v_rcp_f32_e32 v27, v33
	s_nop 0
	v_mul_f32_e32 v1, v1, v27
	s_nop 4
	v_rcp_f32_e32 v27, v32
	s_nop 0
	v_mul_f32_e32 v0, v0, v27
	v_pk_mul_f32 v[0:1], v[2:3], v[0:1]
	v_ashrrev_i32_e32 v29, 31, v28
	v_cvt_pk_bf16_f32 v27, v0, v1
	v_lshl_add_u64 v[0:1], s[6:7], 0, v[28:29]
	v_mad_u64_u32 v[2:3], s[34:35], v0, s49, v[24:25]
	v_mad_i32_i24 v3, v1, s49, v3
	v_cmp_lt_i32_e32 vcc, s50, v28
	global_store_dword v[2:3], v27, off
	s_and_b64 exec, exec, vcc
	s_cbranch_execz .LBB0_841
	v_readlane_b32 s64, v251, 56
	v_add_u32_e32 v0, s10, v36
	v_readlane_b32 s66, v251, 58
	v_readlane_b32 s67, v251, 59
	v_add_u32_e32 v2, 0xfffff800, v0
	v_readlane_b32 s65, v251, 57
	v_mov_b64_e32 v[0:1], s[66:67]
	v_mad_i64_i32 v[0:1], s[34:35], v2, s51, v[0:1]
	v_lshl_add_u64 v[0:1], v[20:21], 2, v[0:1]
	global_store_dwordx2 v[0:1], v[34:35], off
	v_add_co_u32_e32 v0, vcc, 0x2000, v0
	v_readlane_b32 s68, v251, 60
	s_nop 0
	v_addc_co_u32_e32 v1, vcc, 0, v1, vcc
	v_readlane_b32 s69, v251, 61
	v_readlane_b32 s70, v251, 62
	v_readlane_b32 s71, v251, 63
	v_readlane_b32 s72, v252, 0
	v_readlane_b32 s73, v252, 1
	v_readlane_b32 s74, v252, 2
	v_readlane_b32 s75, v252, 3
	v_readlane_b32 s76, v252, 4
	v_readlane_b32 s77, v252, 5
	v_readlane_b32 s78, v252, 6
	v_readlane_b32 s79, v252, 7
	global_store_dwordx2 v[0:1], v[30:31], off offset:3072
.LBB0_841:
	s_or_b64 exec, exec, s[8:9]
	ds_read2_b64 v[40:43], v38 offset0:66 offset1:82
	v_add_u32_e32 v0, -1, v26
	v_cmp_gt_i32_e32 vcc, 0, v0
	s_waitcnt lgkmcnt(0)
	s_nop 0
	v_cndmask_b32_e64 v33, v41, 0, vcc
	v_cndmask_b32_e64 v32, v40, 0, vcc
	v_cndmask_b32_e64 v29, v43, 0, vcc
	v_cndmask_b32_e64 v28, v42, 0, vcc
	v_cmp_gt_i32_e32 vcc, s47, v0
	s_and_b64 s[8:9], s[4:5], vcc
	s_and_saveexec_b64 s[4:5], s[8:9]
	s_cbranch_execz .LBB0_844
	v_pk_mul_f32 v[2:3], v[8:9], v[4:5]
	v_pk_mul_f32 v[6:7], v[14:15], v[6:7]
	v_pk_fma_f32 v[2:3], v[10:11], v[34:35], v[2:3]
	v_pk_fma_f32 v[6:7], v[16:17], v[30:31], v[6:7]
	v_pk_fma_f32 v[2:3], v[12:13], v[32:33], v[2:3]
	v_pk_fma_f32 v[6:7], v[18:19], v[28:29], v[6:7]
	v_mul_f32_e32 v1, 0xbfb8aa3b, v2
	v_exp_f32_e32 v4, v1
	v_mul_f32_e32 v1, 0xbfb8aa3b, v3
	v_exp_f32_e32 v5, v1
	s_nop 0
	v_pk_add_f32 v[4:5], v[4:5], 1.0 op_sel_hi:[1,0]
	s_nop 4
	v_rcp_f32_e32 v1, v5
	s_nop 0
	v_mul_f32_e32 v3, v3, v1
	s_nop 4
	v_rcp_f32_e32 v1, v4
	s_nop 0
	v_mul_f32_e32 v2, v2, v1
	v_pk_mul_f32 v[2:3], v[6:7], v[2:3]
	v_ashrrev_i32_e32 v1, 31, v0
	v_cvt_pk_bf16_f32 v6, v2, v3
	v_lshl_add_u64 v[2:3], s[6:7], 0, v[0:1]
	v_mad_u64_u32 v[4:5], s[8:9], v2, s49, v[24:25]
	v_mad_i32_i24 v5, v3, s49, v5
	v_cmp_lt_i32_e32 vcc, s50, v0
	global_store_dword v[4:5], v6, off
	s_and_b64 exec, exec, vcc
	s_cbranch_execz .LBB0_844
	v_readlane_b32 s64, v251, 56
	v_add_u32_e32 v0, s10, v36
	v_readlane_b32 s66, v251, 58
	v_readlane_b32 s67, v251, 59
	v_add_u32_e32 v2, 0xfffff801, v0
	v_readlane_b32 s65, v251, 57
	v_mov_b64_e32 v[0:1], s[66:67]
	v_mad_i64_i32 v[0:1], s[8:9], v2, s51, v[0:1]
	v_lshl_add_u64 v[0:1], v[20:21], 2, v[0:1]
	global_store_dwordx2 v[0:1], v[32:33], off
	v_add_co_u32_e32 v0, vcc, 0x2000, v0
	v_readlane_b32 s68, v251, 60
	s_nop 0
	v_addc_co_u32_e32 v1, vcc, 0, v1, vcc
	v_readlane_b32 s69, v251, 61
	v_readlane_b32 s70, v251, 62
	v_readlane_b32 s71, v251, 63
	v_readlane_b32 s72, v252, 0
	v_readlane_b32 s73, v252, 1
	v_readlane_b32 s74, v252, 2
	v_readlane_b32 s75, v252, 3
	v_readlane_b32 s76, v252, 4
	v_readlane_b32 s77, v252, 5
	v_readlane_b32 s78, v252, 6
	v_readlane_b32 s79, v252, 7
	global_store_dwordx2 v[0:1], v[28:29], off offset:3072
.LBB0_844:
	s_or_b64 exec, exec, s[4:5]
	ds_read2_b64 v[0:3], v38 offset0:132 offset1:148
	v_cmp_gt_i32_e32 vcc, 0, v26
	s_waitcnt lgkmcnt(0)
	s_nop 0
	v_cndmask_b32_e64 v1, v1, 0, vcc
	v_cndmask_b32_e64 v0, v0, 0, vcc
	v_cndmask_b32_e64 v3, v3, 0, vcc
	v_cndmask_b32_e64 v2, v2, 0, vcc
	v_cmp_gt_i32_e32 vcc, s47, v26
	s_and_saveexec_b64 s[4:5], vcc
	s_cbranch_execz .LBB0_847
	v_pk_mul_f32 v[4:5], v[8:9], v[34:35]
	v_pk_mul_f32 v[30:31], v[14:15], v[30:31]
	v_pk_fma_f32 v[4:5], v[10:11], v[32:33], v[4:5]
	v_pk_fma_f32 v[30:31], v[16:17], v[28:29], v[30:31]
	v_pk_fma_f32 v[4:5], v[12:13], v[0:1], v[4:5]
	v_pk_fma_f32 v[30:31], v[18:19], v[2:3], v[30:31]
	v_mul_f32_e32 v6, 0xbfb8aa3b, v4
	v_mul_f32_e32 v7, 0xbfb8aa3b, v5
	v_exp_f32_e32 v6, v6
	v_exp_f32_e32 v7, v7
	s_nop 0
	v_pk_add_f32 v[6:7], v[6:7], 1.0 op_sel_hi:[1,0]
	s_nop 4
	v_rcp_f32_e32 v27, v7
	s_nop 0
	v_mul_f32_e32 v5, v5, v27
	s_nop 4
	v_rcp_f32_e32 v7, v6
	s_nop 0
	v_mul_f32_e32 v4, v4, v7
	v_pk_mul_f32 v[4:5], v[30:31], v[4:5]
	v_ashrrev_i32_e32 v27, 31, v26
	v_cvt_pk_bf16_f32 v30, v4, v5
	v_lshl_add_u64 v[4:5], s[6:7], 0, v[26:27]
	v_mad_u64_u32 v[6:7], s[8:9], v4, s49, v[24:25]
	v_mad_i32_i24 v7, v5, s49, v7
	v_cmp_lt_i32_e32 vcc, s50, v26
	global_store_dword v[6:7], v30, off
	s_and_b64 exec, exec, vcc
	s_cbranch_execz .LBB0_847
	v_readlane_b32 s64, v251, 56
	v_add_u32_e32 v4, s10, v36
	v_readlane_b32 s66, v251, 58
	v_readlane_b32 s67, v251, 59
	v_add_u32_e32 v6, 0xfffff802, v4
	v_readlane_b32 s65, v251, 57
	v_mov_b64_e32 v[4:5], s[66:67]
	v_mad_i64_i32 v[4:5], s[8:9], v6, s51, v[4:5]
	v_lshl_add_u64 v[4:5], v[20:21], 2, v[4:5]
	global_store_dwordx2 v[4:5], v[0:1], off
	v_add_co_u32_e32 v4, vcc, 0x2000, v4
	v_readlane_b32 s68, v251, 60
	s_nop 0
	v_addc_co_u32_e32 v5, vcc, 0, v5, vcc
	v_readlane_b32 s69, v251, 61
	v_readlane_b32 s70, v251, 62
	v_readlane_b32 s71, v251, 63
	v_readlane_b32 s72, v252, 0
	v_readlane_b32 s73, v252, 1
	v_readlane_b32 s74, v252, 2
	v_readlane_b32 s75, v252, 3
	v_readlane_b32 s76, v252, 4
	v_readlane_b32 s77, v252, 5
	v_readlane_b32 s78, v252, 6
	v_readlane_b32 s79, v252, 7
	global_store_dwordx2 v[4:5], v[2:3], off offset:3072
.LBB0_847:
	s_or_b64 exec, exec, s[4:5]
	ds_read2_b64 v[4:7], v38 offset0:198 offset1:214
	v_add_u32_e32 v26, 1, v26
	v_cmp_gt_i32_e32 vcc, 0, v26
	s_waitcnt lgkmcnt(0)
	s_nop 0
	v_cndmask_b32_e64 v5, v5, 0, vcc
	v_cndmask_b32_e64 v4, v4, 0, vcc
	v_cndmask_b32_e64 v7, v7, 0, vcc
	v_cndmask_b32_e64 v6, v6, 0, vcc
	v_cmp_gt_i32_e32 vcc, s47, v26
	s_and_saveexec_b64 s[4:5], vcc
	s_cbranch_execz .LBB0_837
	v_pk_mul_f32 v[30:31], v[8:9], v[32:33]
	v_pk_mul_f32 v[28:29], v[14:15], v[28:29]
	v_pk_fma_f32 v[30:31], v[10:11], v[0:1], v[30:31]
	v_pk_fma_f32 v[28:29], v[16:17], v[2:3], v[28:29]
	v_pk_fma_f32 v[30:31], v[12:13], v[4:5], v[30:31]
	v_pk_fma_f32 v[28:29], v[18:19], v[6:7], v[28:29]
	v_mul_f32_e32 v27, 0xbfb8aa3b, v30
	v_exp_f32_e32 v32, v27
	v_mul_f32_e32 v27, 0xbfb8aa3b, v31
	v_exp_f32_e32 v33, v27
	s_nop 0
	v_pk_add_f32 v[32:33], v[32:33], 1.0 op_sel_hi:[1,0]
	s_nop 4
	v_rcp_f32_e32 v27, v33
	s_nop 0
	v_mul_f32_e32 v31, v31, v27
	s_nop 4
	v_rcp_f32_e32 v27, v32
	s_nop 0
	v_mul_f32_e32 v30, v30, v27
	v_pk_mul_f32 v[28:29], v[28:29], v[30:31]
	v_ashrrev_i32_e32 v27, 31, v26
	v_cvt_pk_bf16_f32 v32, v28, v29
	v_lshl_add_u64 v[28:29], s[6:7], 0, v[26:27]
	v_mad_u64_u32 v[30:31], s[8:9], v28, s49, v[24:25]
	v_mad_i32_i24 v31, v29, s49, v31
	v_cmp_lt_i32_e32 vcc, s50, v26
	global_store_dword v[30:31], v32, off
	s_and_b64 exec, exec, vcc
	s_cbranch_execz .LBB0_837
	v_readlane_b32 s64, v251, 56
	v_add_u32_e32 v26, s10, v36
	v_readlane_b32 s66, v251, 58
	v_readlane_b32 s67, v251, 59
	v_add_u32_e32 v28, 0xfffff803, v26
	v_readlane_b32 s65, v251, 57
	v_mov_b64_e32 v[26:27], s[66:67]
	v_mad_i64_i32 v[26:27], s[8:9], v28, s51, v[26:27]
	v_lshl_add_u64 v[26:27], v[20:21], 2, v[26:27]
	global_store_dwordx2 v[26:27], v[4:5], off
	v_add_co_u32_e32 v26, vcc, 0x2000, v26
	v_readlane_b32 s68, v251, 60
	s_nop 0
	v_addc_co_u32_e32 v27, vcc, 0, v27, vcc
	v_readlane_b32 s69, v251, 61
	v_readlane_b32 s70, v251, 62
	v_readlane_b32 s71, v251, 63
	v_readlane_b32 s72, v252, 0
	v_readlane_b32 s73, v252, 1
	v_readlane_b32 s74, v252, 2
	v_readlane_b32 s75, v252, 3
	v_readlane_b32 s76, v252, 4
	v_readlane_b32 s77, v252, 5
	v_readlane_b32 s78, v252, 6
	v_readlane_b32 s79, v252, 7
	global_store_dwordx2 v[26:27], v[6:7], off offset:3072
	s_branch .LBB0_837

.LBB0_854:
	v_add_co_u32_e32 v28, vcc, s55, v0
	v_lshl_add_u64 v[26:27], v[4:5], 0, s[6:7]
	s_nop 0
	v_addc_co_u32_e32 v29, vcc, -1, v1, vcc
	v_add_co_u32_e32 v30, vcc, 0x5000, v26
	ds_read2_b64 v[22:25], v20 offset1:16
	s_nop 0
	v_addc_co_u32_e32 v31, vcc, 0, v27, vcc
	v_add_co_u32_e32 v42, vcc, 0x8000, v26
	global_load_dwordx2 v[30:31], v[30:31], off offset:2048
	s_nop 0
	v_addc_co_u32_e32 v43, vcc, 0, v27, vcc
	v_add_co_u32_e32 v44, vcc, s52, v26
	v_lshl_add_u64 v[6:7], v[2:3], 0, s[6:7]
	s_nop 0
	v_addc_co_u32_e32 v45, vcc, 0, v27, vcc
	global_load_dwordx2 v[42:43], v[42:43], off offset:1024
	s_nop 0
	global_load_dwordx2 v[44:45], v[44:45], off offset:3072
	s_nop 0
	global_load_dwordx2 v[46:47], v[26:27], off
	v_add_co_u32_e64 v32, s[4:5], s52, v6
	v_add_co_u32_e32 v48, vcc, s59, v26
	s_nop 0
	v_addc_co_u32_e64 v33, s[4:5], 0, v7, s[4:5]
	v_add_co_u32_e64 v34, s[4:5], s53, v6
	v_addc_co_u32_e32 v49, vcc, 0, v27, vcc
	s_nop 0
	v_addc_co_u32_e64 v35, s[4:5], 0, v7, s[4:5]
	v_add_co_u32_e64 v36, s[4:5], s54, v6
	s_add_u32 s6, s6, 0x16000
	s_nop 0
	v_addc_co_u32_e64 v37, s[4:5], 0, v7, s[4:5]
	v_add_co_u32_e64 v38, s[4:5], s48, v26
	s_addc_u32 s7, s7, 0
	s_nop 0
	v_addc_co_u32_e64 v39, s[4:5], 0, v27, s[4:5]
	v_add_co_u32_e64 v40, s[4:5], s58, v26
	v_add_co_u32_e32 v26, vcc, s60, v26
	s_nop 0
	v_addc_co_u32_e64 v41, s[4:5], 0, v27, s[4:5]
	v_addc_co_u32_e32 v27, vcc, 0, v27, vcc
	s_cmp_eq_u32 s6, 0xb0000
	s_waitcnt vmcnt(3)
	v_pk_mul_f32 v[50:51], v[10:11], v[30:31]
	s_waitcnt vmcnt(2)
	v_pk_mul_f32 v[52:53], v[16:17], v[42:43]
	s_waitcnt vmcnt(1)
	v_pk_fma_f32 v[44:45], v[14:15], v[44:45], v[52:53]
	s_waitcnt vmcnt(0)
	v_pk_fma_f32 v[46:47], v[8:9], v[46:47], v[50:51]
	s_waitcnt lgkmcnt(0)
	v_pk_fma_f32 v[44:45], v[18:19], v[24:25], v[44:45]
	v_pk_fma_f32 v[46:47], v[12:13], v[22:23], v[46:47]
	s_nop 0
	v_mul_f32_e32 v21, 0xbfb8aa3b, v46
	v_mul_f32_e32 v51, 0xbfb8aa3b, v47
	v_exp_f32_e32 v50, v21
	v_exp_f32_e32 v51, v51
	s_nop 0
	v_pk_add_f32 v[50:51], v[50:51], 1.0 op_sel_hi:[1,0]
	s_nop 4
	s_mov_b64 vcc, s[4:5]
	v_rcp_f32_e32 v21, v51
	s_nop 0
	v_mul_f32_e32 v47, v47, v21
	s_nop 0
	v_rcp_f32_e32 v21, v50
	s_nop 0
	v_mul_f32_e32 v46, v46, v21
	v_pk_mul_f32 v[44:45], v[44:45], v[46:47]
	s_nop 0
	v_cvt_pk_bf16_f32 v21, v44, v45
	global_store_dword v[28:29], v21, off offset:-1536
	global_store_dwordx2 v[6:7], v[30:31], off
	global_store_dwordx2 v[32:33], v[42:43], off offset:3072
	global_store_dwordx2 v[34:35], v[22:23], off offset:2048
	global_store_dwordx2 v[36:37], v[24:25], off offset:1024
	global_load_dwordx2 v[28:29], v[38:39], off offset:2048
	s_nop 0
	global_load_dwordx2 v[30:31], v[40:41], off offset:1024
	global_load_dwordx2 v[32:33], v[48:49], off
	s_nop 0
	global_load_dwordx2 v[26:27], v[26:27], off offset:3072
	ds_read2_b64 v[22:25], v20 offset0:66 offset1:82
	v_add_u32_e32 v20, 0x420, v20
	s_waitcnt vmcnt(3)
	v_pk_mul_f32 v[34:35], v[10:11], v[28:29]
	s_waitcnt vmcnt(2)
	v_pk_mul_f32 v[36:37], v[16:17], v[30:31]
	s_waitcnt vmcnt(1)
	v_pk_fma_f32 v[32:33], v[8:9], v[32:33], v[34:35]
	s_waitcnt vmcnt(0)
	v_pk_fma_f32 v[26:27], v[14:15], v[26:27], v[36:37]
	s_waitcnt lgkmcnt(0)
	v_pk_fma_f32 v[32:33], v[12:13], v[22:23], v[32:33]
	v_pk_fma_f32 v[26:27], v[18:19], v[24:25], v[26:27]
	v_mul_f32_e32 v21, 0xbfb8aa3b, v32
	v_mul_f32_e32 v35, 0xbfb8aa3b, v33
	v_exp_f32_e32 v34, v21
	v_exp_f32_e32 v35, v35
	s_nop 0
	v_pk_add_f32 v[34:35], v[34:35], 1.0 op_sel_hi:[1,0]
	s_nop 4
	s_mov_b64 vcc, s[4:5]
	v_rcp_f32_e32 v21, v35
	s_nop 0
	v_mul_f32_e32 v33, v33, v21
	s_nop 0
	v_add_co_u32_e32 v36, vcc, s59, v6
	v_rcp_f32_e32 v21, v34
	s_nop 0
	v_mul_f32_e32 v32, v32, v21
	s_nop 0
	v_addc_co_u32_e32 v37, vcc, 0, v7, vcc
	v_add_co_u32_e32 v34, vcc, s60, v6
	v_pk_mul_f32 v[26:27], v[26:27], v[32:33]
	s_nop 0
	v_addc_co_u32_e32 v35, vcc, 0, v7, vcc
	v_add_co_u32_e32 v32, vcc, s48, v6
	v_cvt_pk_bf16_f32 v21, v26, v27
	s_nop 0
	v_addc_co_u32_e32 v33, vcc, 0, v7, vcc
	v_add_co_u32_e32 v6, vcc, s58, v6
	global_store_dword v[0:1], v21, off
	global_store_dwordx2 v[36:37], v[28:29], off
	global_store_dwordx2 v[34:35], v[30:31], off offset:3072
	global_store_dwordx2 v[32:33], v[22:23], off offset:2048
	v_addc_co_u32_e32 v7, vcc, 0, v7, vcc
	v_lshl_add_u64 v[0:1], v[0:1], 0, s[24:25]
	global_store_dwordx2 v[6:7], v[24:25], off offset:1024
	s_cbranch_scc0 .LBB0_854
	s_branch .LBB0_797
